# GEMM sub-phases: vmcnt and lgkmcnt waits before each barrier merged into one s_waitcnt (20 sites)
# baseline (speedup 1.0000x reference)
; #define PG8_STAGE(bufoff, gbase, voff) do { _Pragma("unroll") for (int _i = 0; _i < 2; ++_i) \
;         __builtin_amdgcn_global_load_lds((const unsigned*)((const char*)(gbase) + (voff)[_i]), (LAS unsigned*)(lds + (bufoff) + ldsw + _i * 8192), 16, 0, 0); } while (0)
; #define PG8_LDA(dst, b, h) do { _Pragma("unroll") for (int m = 0; m < 4; ++m) _Pragma("unroll") for (int k = 0; k < 2; ++k) dst[m][k] = *(const LAS bf16x8*)(lds + PG8_SA(b, h) + aoff + m * 2048 + k * 1024); } while (0)
; #define PG8_LDB(dst, b, h) do { _Pragma("unroll") for (int n = 0; n < 2; ++n) _Pragma("unroll") for (int k = 0; k < 2; ++k) dst[n][k] = *(const LAS bf16x8*)(lds + PG8_SB(b, h) + boff + n * 2048 + k * 1024); } while (0)
; #define PG8_MMA(ai, bj, At, Bt) do { __builtin_amdgcn_s_setprio(1); _Pragma("unroll") for (int m = 0; m < 4; ++m) _Pragma("unroll") for (int n = 0; n < 2; ++n) _Pragma("unroll") for (int k = 0; k < 2; ++k) \
;         acc[ai][bj][m][n] = __builtin_amdgcn_mfma_f32_16x16x32_bf16(Bt[n][k], At[m][k], acc[ai][bj][m][n], 0, 0, 0); __builtin_amdgcn_s_setprio(0); } while (0)
; #define PG8_WAIT_V(n) asm volatile("s_waitcnt vmcnt(" #n ")" ::: "memory")
; #define PG8_WAIT_L(n) asm volatile("s_waitcnt lgkmcnt(" #n ")" ::: "memory")
; #define PG8_BAR __builtin_amdgcn_s_barrier()
; #define PG8_SCHED __builtin_amdgcn_sched_barrier(0)
; template <class Epi, class Sched>
; DI void gemm_phase(const int wv, LAS unsigned char* lds, const int lda, const int ldb, const int K, const Sched& S, const Epi& E) {
;     ...
;             const bool last = (t == nt - 2);
;             const char* a1 = cA + (size_t)(t + 1) * kstep;
;             const char* a2 = last ? nA : cA + (size_t)(t + 2) * kstep; const char* b2 = last ? nB : cB + (size_t)(t + 2) * kstep;
;             const char* a3 = a2 + kstep; const char* b3 = b2 + kstep;
;             PG8_LDB(B0, 0, 0); PG8_LDB(B1, 0, 1); PG8_SCHED; PG8_LDA(At, 0, 0); PG8_STAGE(PG8_SA(1, 1), a1 + hstepA, voffA);
;             PG8_WAIT_V(8); PG8_WAIT_L(0); PG8_BAR; PG8_MMA(0, 0, At, B0); PG8_MMA(0, 1, At, B1); PG8_BAR; PG8_SCHED;
;             PG8_LDA(At, 0, 1); PG8_STAGE(PG8_SB(0, 0), b2, voffB); PG8_STAGE(PG8_SB(0, 1), b2 + hstepB, voffB); PG8_STAGE(PG8_SA(0, 0), a2, voffA);
;             PG8_WAIT_V(8); PG8_WAIT_L(0); PG8_BAR; PG8_MMA(1, 0, At, B0); PG8_MMA(1, 1, At, B1); PG8_BAR; PG8_SCHED;
.LBB0_285:
	s_add_u32 s20, s18, 0xfff80080
	s_addc_u32 s21, s19, -1
	s_add_i32 s42, 0, 0x10000
	s_cmp_eq_u32 s41, 28
	s_cselect_b32 s23, s15, s21
	s_cselect_b32 s22, s14, s20
	v_add_u32_e32 v143, s42, v139
	s_cselect_b32 s21, s17, s40
	s_cselect_b32 s20, s16, s13
	s_add_i32 s44, 0, 0x14000
	ds_read_b128 v[144:147], v143
	ds_read_b128 v[148:151], v143 offset:1024
	ds_read_b128 v[152:155], v143 offset:2048
	ds_read_b128 v[156:159], v143 offset:3072
	v_add_u32_e32 v143, s44, v139
	ds_read_b128 v[168:171], v143
	ds_read_b128 v[172:175], v143 offset:1024
	ds_read_b128 v[176:179], v143 offset:2048
	ds_read_b128 v[180:183], v143 offset:3072
	v_lshl_add_u64 v[162:163], s[18:19], 0, v[136:137]
	s_add_i32 m0, s29, 0xc000
	ds_read_b128 v[184:187], v142
	ds_read_b128 v[188:191], v142 offset:1024
	ds_read_b128 v[192:195], v142 offset:2048
	ds_read_b128 v[196:199], v142 offset:3072
	ds_read_b128 v[210:213], v142 offset:4096
	ds_read_b128 v[214:217], v142 offset:5120
	ds_read_b128 v[218:221], v142 offset:6144
	ds_read_b128 v[222:225], v142 offset:7168
	global_load_lds_dwordx4 v[162:163], off
	v_lshl_add_u64 v[162:163], s[18:19], 0, v[134:135]
	s_add_i32 m0, s29, 0xe000
	s_nop 0
	global_load_lds_dwordx4 v[162:163], off
	s_waitcnt vmcnt(8) lgkmcnt(0)
	s_barrier
	s_setprio 1
	v_mfma_f32_16x16x32_bf16 v[124:127], v[144:147], v[184:187], v[124:127]
	v_mfma_f32_16x16x32_bf16 v[120:123], v[152:155], v[184:187], v[120:123]
	v_mfma_f32_16x16x32_bf16 v[116:119], v[144:147], v[192:195], v[116:119]
	v_mfma_f32_16x16x32_bf16 v[112:115], v[152:155], v[192:195], v[112:115]
	v_mfma_f32_16x16x32_bf16 v[100:103], v[144:147], v[210:213], v[100:103]
	v_mfma_f32_16x16x32_bf16 v[96:99], v[152:155], v[210:213], v[96:99]
	v_mfma_f32_16x16x32_bf16 v[88:91], v[144:147], v[218:221], v[88:91]
	v_mfma_f32_16x16x32_bf16 v[80:83], v[152:155], v[218:221], v[80:83]
	v_mfma_f32_16x16x32_bf16 v[124:127], v[148:151], v[188:191], v[124:127]
	v_mfma_f32_16x16x32_bf16 v[120:123], v[156:159], v[188:191], v[120:123]
	v_mfma_f32_16x16x32_bf16 v[116:119], v[148:151], v[196:199], v[116:119]
	v_mfma_f32_16x16x32_bf16 v[112:115], v[156:159], v[196:199], v[112:115]
	v_mfma_f32_16x16x32_bf16 v[100:103], v[148:151], v[214:217], v[100:103]
	v_mfma_f32_16x16x32_bf16 v[96:99], v[156:159], v[214:217], v[96:99]
	v_mfma_f32_16x16x32_bf16 v[88:91], v[148:151], v[222:225], v[88:91]
	v_mfma_f32_16x16x32_bf16 v[80:83], v[156:159], v[222:225], v[80:83]
	v_mfma_f32_16x16x32_bf16 v[108:111], v[168:171], v[184:187], v[108:111]
	v_mfma_f32_16x16x32_bf16 v[104:107], v[176:179], v[184:187], v[104:107]
	v_mfma_f32_16x16x32_bf16 v[92:95], v[168:171], v[192:195], v[92:95]
	v_mfma_f32_16x16x32_bf16 v[84:87], v[176:179], v[192:195], v[84:87]
	v_mfma_f32_16x16x32_bf16 v[76:79], v[168:171], v[210:213], v[76:79]
	v_mfma_f32_16x16x32_bf16 v[72:75], v[176:179], v[210:213], v[72:75]
	v_mfma_f32_16x16x32_bf16 v[68:71], v[168:171], v[218:221], v[68:71]
	v_mfma_f32_16x16x32_bf16 v[64:67], v[176:179], v[218:221], v[64:67]
	v_mfma_f32_16x16x32_bf16 v[108:111], v[172:175], v[188:191], v[108:111]
	v_mfma_f32_16x16x32_bf16 v[104:107], v[180:183], v[188:191], v[104:107]
	v_mfma_f32_16x16x32_bf16 v[92:95], v[172:175], v[196:199], v[92:95]
	v_mfma_f32_16x16x32_bf16 v[84:87], v[180:183], v[196:199], v[84:87]
	v_mfma_f32_16x16x32_bf16 v[76:79], v[172:175], v[214:217], v[76:79]
	v_mfma_f32_16x16x32_bf16 v[72:75], v[180:183], v[214:217], v[72:75]
	v_mfma_f32_16x16x32_bf16 v[68:71], v[172:175], v[222:225], v[68:71]
	v_mfma_f32_16x16x32_bf16 v[64:67], v[180:183], v[222:225], v[64:67]
	s_setprio 0
	s_barrier
	s_add_i32 s42, s42, s28
	v_lshl_add_u64 v[162:163], s[20:21], 0, v[160:161]
	s_mov_b32 m0, s42
	ds_read_b128 v[184:187], v142 offset:16384
	ds_read_b128 v[188:191], v142 offset:17408
	ds_read_b128 v[192:195], v142 offset:18432
	ds_read_b128 v[196:199], v142 offset:19456
	ds_read_b128 v[210:213], v142 offset:20480
	ds_read_b128 v[214:217], v142 offset:21504
	ds_read_b128 v[218:221], v142 offset:22528
	ds_read_b128 v[222:225], v142 offset:23552
	global_load_lds_dwordx4 v[162:163], off
	s_add_i32 m0, s42, 0x2000
	s_add_u32 s42, s20, 0x80000
	v_lshl_add_u64 v[164:165], s[20:21], 0, v[128:129]
	s_addc_u32 s43, s21, 0
	s_add_i32 s44, s44, s28
	global_load_lds_dwordx4 v[164:165], off
	v_lshl_add_u64 v[226:227], s[42:43], 0, v[160:161]
	s_mov_b32 m0, s44
	v_lshl_add_u64 v[228:229], s[22:23], 0, v[130:131]
	global_load_lds_dwordx4 v[226:227], off
	v_lshl_add_u64 v[226:227], s[42:43], 0, v[128:129]
	s_add_i32 m0, s44, 0x2000
	s_nop 0
	global_load_lds_dwordx4 v[226:227], off
	v_lshl_add_u64 v[226:227], s[22:23], 0, v[132:133]
	s_mov_b32 m0, s29
	s_nop 0
	global_load_lds_dwordx4 v[226:227], off
	s_mov_b32 m0, s30
	s_nop 0
	global_load_lds_dwordx4 v[228:229], off
	s_waitcnt vmcnt(8) lgkmcnt(0)
	s_barrier
; #define PG8_STAGE(bufoff, gbase, voff) do { _Pragma("unroll") for (int _i = 0; _i < 2; ++_i) \
;         __builtin_amdgcn_global_load_lds((const unsigned*)((const char*)(gbase) + (voff)[_i]), (LAS unsigned*)(lds + (bufoff) + ldsw + _i * 8192), 16, 0, 0); } while (0)
; #define PG8_LDA(dst, b, h) do { _Pragma("unroll") for (int m = 0; m < 4; ++m) _Pragma("unroll") for (int k = 0; k < 2; ++k) dst[m][k] = *(const LAS bf16x8*)(lds + PG8_SA(b, h) + aoff + m * 2048 + k * 1024); } while (0)
; #define PG8_LDB(dst, b, h) do { _Pragma("unroll") for (int n = 0; n < 2; ++n) _Pragma("unroll") for (int k = 0; k < 2; ++k) dst[n][k] = *(const LAS bf16x8*)(lds + PG8_SB(b, h) + boff + n * 2048 + k * 1024); } while (0)
; #define PG8_MMA(ai, bj, At, Bt) do { __builtin_amdgcn_s_setprio(1); _Pragma("unroll") for (int m = 0; m < 4; ++m) _Pragma("unroll") for (int n = 0; n < 2; ++n) _Pragma("unroll") for (int k = 0; k < 2; ++k) \
;         acc[ai][bj][m][n] = __builtin_amdgcn_mfma_f32_16x16x32_bf16(Bt[n][k], At[m][k], acc[ai][bj][m][n], 0, 0, 0); __builtin_amdgcn_s_setprio(0); } while (0)
; #define PG8_WAIT_V(n) asm volatile("s_waitcnt vmcnt(" #n ")" ::: "memory")
; #define PG8_WAIT_L(n) asm volatile("s_waitcnt lgkmcnt(" #n ")" ::: "memory")
; #define PG8_BAR __builtin_amdgcn_s_barrier()
; #define PG8_SCHED __builtin_amdgcn_sched_barrier(0)
; template <class Epi, class Sched>
; DI void gemm_phase(const int wv, LAS unsigned char* lds, const int lda, const int ldb, const int K, const Sched& S, const Epi& E) {
;     ...
;             PG8_WAIT_V(8); PG8_WAIT_L(0); PG8_BAR; PG8_MMA(1, 0, At, B0); PG8_MMA(1, 1, At, B1); PG8_BAR; PG8_SCHED;
;             PG8_LDB(B0, 1, 0); PG8_LDB(B1, 1, 1); PG8_SCHED; PG8_LDA(At, 1, 0); PG8_STAGE(PG8_SA(0, 1), a2 + hstepA, voffA);
;             PG8_WAIT_V(8); PG8_WAIT_L(0); PG8_BAR; PG8_MMA(0, 0, At, B0); PG8_MMA(0, 1, At, B1); PG8_BAR; PG8_SCHED;
	s_setprio 1
	v_mfma_f32_16x16x32_bf16 v[60:63], v[144:147], v[184:187], v[60:63]
	v_mfma_f32_16x16x32_bf16 v[56:59], v[152:155], v[184:187], v[56:59]
	v_mfma_f32_16x16x32_bf16 v[52:55], v[144:147], v[192:195], v[52:55]
	v_mfma_f32_16x16x32_bf16 v[48:51], v[152:155], v[192:195], v[48:51]
	v_mfma_f32_16x16x32_bf16 v[44:47], v[144:147], v[210:213], v[44:47]
	v_mfma_f32_16x16x32_bf16 v[36:39], v[152:155], v[210:213], v[36:39]
	v_mfma_f32_16x16x32_bf16 v[28:31], v[144:147], v[218:221], v[28:31]
	v_mfma_f32_16x16x32_bf16 v[20:23], v[152:155], v[218:221], v[20:23]
	v_mfma_f32_16x16x32_bf16 v[60:63], v[148:151], v[188:191], v[60:63]
	v_mfma_f32_16x16x32_bf16 v[56:59], v[156:159], v[188:191], v[56:59]
	v_mfma_f32_16x16x32_bf16 v[52:55], v[148:151], v[196:199], v[52:55]
	v_mfma_f32_16x16x32_bf16 v[48:51], v[156:159], v[196:199], v[48:51]
	v_mfma_f32_16x16x32_bf16 v[44:47], v[148:151], v[214:217], v[44:47]
	v_mfma_f32_16x16x32_bf16 v[36:39], v[156:159], v[214:217], v[36:39]
	v_mfma_f32_16x16x32_bf16 v[28:31], v[148:151], v[222:225], v[28:31]
	v_mfma_f32_16x16x32_bf16 v[20:23], v[156:159], v[222:225], v[20:23]
	v_mfma_f32_16x16x32_bf16 v[40:43], v[168:171], v[184:187], v[40:43]
	v_mfma_f32_16x16x32_bf16 v[32:35], v[176:179], v[184:187], v[32:35]
	v_mfma_f32_16x16x32_bf16 v[24:27], v[168:171], v[192:195], v[24:27]
	v_mfma_f32_16x16x32_bf16 v[16:19], v[176:179], v[192:195], v[16:19]
	v_mfma_f32_16x16x32_bf16 v[12:15], v[168:171], v[210:213], v[12:15]
	v_mfma_f32_16x16x32_bf16 v[8:11], v[176:179], v[210:213], v[8:11]
	v_mfma_f32_16x16x32_bf16 v[4:7], v[168:171], v[218:221], v[4:7]
	v_mfma_f32_16x16x32_bf16 v[0:3], v[176:179], v[218:221], v[0:3]
	v_mfma_f32_16x16x32_bf16 v[40:43], v[172:175], v[188:191], v[40:43]
	v_mfma_f32_16x16x32_bf16 v[32:35], v[180:183], v[188:191], v[32:35]
	v_mfma_f32_16x16x32_bf16 v[24:27], v[172:175], v[196:199], v[24:27]
	v_mfma_f32_16x16x32_bf16 v[16:19], v[180:183], v[196:199], v[16:19]
	v_mfma_f32_16x16x32_bf16 v[12:15], v[172:175], v[214:217], v[12:15]
	v_mfma_f32_16x16x32_bf16 v[8:11], v[180:183], v[214:217], v[8:11]
	v_mfma_f32_16x16x32_bf16 v[4:7], v[172:175], v[222:225], v[4:7]
	v_mfma_f32_16x16x32_bf16 v[0:3], v[180:183], v[222:225], v[0:3]
	s_setprio 0
	s_barrier
	s_add_i32 s42, 0, 0x18000
	v_add_u32_e32 v143, s42, v139
	s_add_i32 s43, 0, 0x1c000
	ds_read_b128 v[144:147], v143
	ds_read_b128 v[148:151], v143 offset:1024
	ds_read_b128 v[152:155], v143 offset:2048
	ds_read_b128 v[156:159], v143 offset:3072
	v_add_u32_e32 v143, s43, v139
	ds_read_b128 v[168:171], v143
	ds_read_b128 v[172:175], v143 offset:1024
	ds_read_b128 v[176:179], v143 offset:2048
	ds_read_b128 v[180:183], v143 offset:3072
	s_add_u32 s22, s22, 0x80000
	s_addc_u32 s23, s23, 0
	s_mov_b32 m0, s31
	v_lshl_add_u64 v[230:231], s[22:23], 0, v[132:133]
	ds_read_b128 v[184:187], v142 offset:32768
	ds_read_b128 v[188:191], v142 offset:33792
	ds_read_b128 v[192:195], v142 offset:34816
	ds_read_b128 v[196:199], v142 offset:35840
	ds_read_b128 v[210:213], v142 offset:36864
	ds_read_b128 v[214:217], v142 offset:37888
	ds_read_b128 v[218:221], v142 offset:38912
	ds_read_b128 v[222:225], v142 offset:39936
	global_load_lds_dwordx4 v[230:231], off
	v_lshl_add_u64 v[230:231], s[22:23], 0, v[130:131]
	s_mov_b32 m0, s34
	s_nop 0
	global_load_lds_dwordx4 v[230:231], off
	s_waitcnt vmcnt(8) lgkmcnt(0)
	s_barrier
	s_setprio 1
	v_mfma_f32_16x16x32_bf16 v[124:127], v[144:147], v[184:187], v[124:127]
	v_mfma_f32_16x16x32_bf16 v[120:123], v[152:155], v[184:187], v[120:123]
	v_mfma_f32_16x16x32_bf16 v[116:119], v[144:147], v[192:195], v[116:119]
	v_mfma_f32_16x16x32_bf16 v[112:115], v[152:155], v[192:195], v[112:115]
	v_mfma_f32_16x16x32_bf16 v[100:103], v[144:147], v[210:213], v[100:103]
	v_mfma_f32_16x16x32_bf16 v[96:99], v[152:155], v[210:213], v[96:99]
	v_mfma_f32_16x16x32_bf16 v[88:91], v[144:147], v[218:221], v[88:91]
	v_mfma_f32_16x16x32_bf16 v[80:83], v[152:155], v[218:221], v[80:83]
	v_mfma_f32_16x16x32_bf16 v[124:127], v[148:151], v[188:191], v[124:127]
	v_mfma_f32_16x16x32_bf16 v[120:123], v[156:159], v[188:191], v[120:123]
	v_mfma_f32_16x16x32_bf16 v[116:119], v[148:151], v[196:199], v[116:119]
	v_mfma_f32_16x16x32_bf16 v[112:115], v[156:159], v[196:199], v[112:115]
	v_mfma_f32_16x16x32_bf16 v[100:103], v[148:151], v[214:217], v[100:103]
	v_mfma_f32_16x16x32_bf16 v[96:99], v[156:159], v[214:217], v[96:99]
	v_mfma_f32_16x16x32_bf16 v[88:91], v[148:151], v[222:225], v[88:91]
	v_mfma_f32_16x16x32_bf16 v[80:83], v[156:159], v[222:225], v[80:83]
	v_mfma_f32_16x16x32_bf16 v[108:111], v[168:171], v[184:187], v[108:111]
	v_mfma_f32_16x16x32_bf16 v[104:107], v[176:179], v[184:187], v[104:107]
	v_mfma_f32_16x16x32_bf16 v[92:95], v[168:171], v[192:195], v[92:95]
	v_mfma_f32_16x16x32_bf16 v[84:87], v[176:179], v[192:195], v[84:87]
	v_mfma_f32_16x16x32_bf16 v[76:79], v[168:171], v[210:213], v[76:79]
	v_mfma_f32_16x16x32_bf16 v[72:75], v[176:179], v[210:213], v[72:75]
	v_mfma_f32_16x16x32_bf16 v[68:71], v[168:171], v[218:221], v[68:71]
	v_mfma_f32_16x16x32_bf16 v[64:67], v[176:179], v[218:221], v[64:67]
	v_mfma_f32_16x16x32_bf16 v[108:111], v[172:175], v[188:191], v[108:111]
	v_mfma_f32_16x16x32_bf16 v[104:107], v[180:183], v[188:191], v[104:107]
	v_mfma_f32_16x16x32_bf16 v[92:95], v[172:175], v[196:199], v[92:95]
	v_mfma_f32_16x16x32_bf16 v[84:87], v[180:183], v[196:199], v[84:87]
	v_mfma_f32_16x16x32_bf16 v[76:79], v[172:175], v[214:217], v[76:79]
	v_mfma_f32_16x16x32_bf16 v[72:75], v[180:183], v[214:217], v[72:75]
	v_mfma_f32_16x16x32_bf16 v[68:71], v[172:175], v[222:225], v[68:71]
	v_mfma_f32_16x16x32_bf16 v[64:67], v[180:183], v[222:225], v[64:67]
	s_setprio 0
	s_barrier
; #define PG8_STAGE(bufoff, gbase, voff) do { _Pragma("unroll") for (int _i = 0; _i < 2; ++_i) \
;         __builtin_amdgcn_global_load_lds((const unsigned*)((const char*)(gbase) + (voff)[_i]), (LAS unsigned*)(lds + (bufoff) + ldsw + _i * 8192), 16, 0, 0); } while (0)
; #define PG8_LDA(dst, b, h) do { _Pragma("unroll") for (int m = 0; m < 4; ++m) _Pragma("unroll") for (int k = 0; k < 2; ++k) dst[m][k] = *(const LAS bf16x8*)(lds + PG8_SA(b, h) + aoff + m * 2048 + k * 1024); } while (0)
; #define PG8_MMA(ai, bj, At, Bt) do { __builtin_amdgcn_s_setprio(1); _Pragma("unroll") for (int m = 0; m < 4; ++m) _Pragma("unroll") for (int n = 0; n < 2; ++n) _Pragma("unroll") for (int k = 0; k < 2; ++k) \
;         acc[ai][bj][m][n] = __builtin_amdgcn_mfma_f32_16x16x32_bf16(Bt[n][k], At[m][k], acc[ai][bj][m][n], 0, 0, 0); __builtin_amdgcn_s_setprio(0); } while (0)
; #define PG8_WAIT_V(n) asm volatile("s_waitcnt vmcnt(" #n ")" ::: "memory")
; #define PG8_WAIT_L(n) asm volatile("s_waitcnt lgkmcnt(" #n ")" ::: "memory")
; #define PG8_BAR __builtin_amdgcn_s_barrier()
; #define PG8_SCHED __builtin_amdgcn_sched_barrier(0)
; template <class Epi, class Sched>
; DI void gemm_phase(const int wv, LAS unsigned char* lds, const int lda, const int ldb, const int K, const Sched& S, const Epi& E) {
;     ...
;             PG8_LDA(At, 1, 1); PG8_STAGE(PG8_SB(1, 0), b3, voffB); PG8_STAGE(PG8_SB(1, 1), b3 + hstepB, voffB); PG8_STAGE(PG8_SA(1, 0), a3, voffA);
;             PG8_WAIT_V(8); PG8_WAIT_L(0); PG8_BAR; PG8_MMA(1, 0, At, B0); PG8_MMA(1, 1, At, B1); PG8_BAR; PG8_SCHED;
;         }
;         if (wr == 0) PG8_BAR;
	s_add_i32 s22, s42, s28
	v_lshl_add_u64 v[162:163], v[162:163], 0, s[78:79]
	s_mov_b32 m0, s22
	ds_read_b128 v[184:187], v142 offset:49152
	ds_read_b128 v[188:191], v142 offset:50176
	ds_read_b128 v[192:195], v142 offset:51200
	ds_read_b128 v[196:199], v142 offset:52224
	ds_read_b128 v[210:213], v142 offset:53248
	ds_read_b128 v[214:217], v142 offset:54272
	ds_read_b128 v[218:221], v142 offset:55296
	ds_read_b128 v[222:225], v142 offset:56320
	global_load_lds_dwordx4 v[162:163], off
	s_add_i32 m0, s22, 0x2000
	s_add_u32 s20, s20, 0x80080
	v_lshl_add_u64 v[162:163], v[164:165], 0, s[78:79]
	s_addc_u32 s21, s21, 0
	s_add_i32 s22, s43, s28
	global_load_lds_dwordx4 v[162:163], off
	v_lshl_add_u64 v[162:163], s[20:21], 0, v[160:161]
	s_mov_b32 m0, s22
	s_nop 0
	global_load_lds_dwordx4 v[162:163], off
	v_lshl_add_u64 v[162:163], s[20:21], 0, v[128:129]
	s_add_i32 m0, s22, 0x2000
	s_nop 0
	global_load_lds_dwordx4 v[162:163], off
	v_lshl_add_u64 v[162:163], v[226:227], 0, s[78:79]
	s_mov_b32 m0, s35
	s_nop 0
	global_load_lds_dwordx4 v[162:163], off
	v_lshl_add_u64 v[162:163], v[228:229], 0, s[78:79]
	s_mov_b32 m0, s36
	s_nop 0
	global_load_lds_dwordx4 v[162:163], off
	s_waitcnt vmcnt(8) lgkmcnt(0)
	s_barrier
	s_setprio 1
	v_mfma_f32_16x16x32_bf16 v[60:63], v[144:147], v[184:187], v[60:63]
	v_mfma_f32_16x16x32_bf16 v[56:59], v[152:155], v[184:187], v[56:59]
	v_mfma_f32_16x16x32_bf16 v[52:55], v[144:147], v[192:195], v[52:55]
	v_mfma_f32_16x16x32_bf16 v[48:51], v[152:155], v[192:195], v[48:51]
	v_mfma_f32_16x16x32_bf16 v[44:47], v[144:147], v[210:213], v[44:47]
	v_mfma_f32_16x16x32_bf16 v[36:39], v[152:155], v[210:213], v[36:39]
	v_mfma_f32_16x16x32_bf16 v[28:31], v[144:147], v[218:221], v[28:31]
	v_mfma_f32_16x16x32_bf16 v[20:23], v[152:155], v[218:221], v[20:23]
	v_mfma_f32_16x16x32_bf16 v[60:63], v[148:151], v[188:191], v[60:63]
	v_mfma_f32_16x16x32_bf16 v[56:59], v[156:159], v[188:191], v[56:59]
	v_mfma_f32_16x16x32_bf16 v[52:55], v[148:151], v[196:199], v[52:55]
	v_mfma_f32_16x16x32_bf16 v[48:51], v[156:159], v[196:199], v[48:51]
	v_mfma_f32_16x16x32_bf16 v[44:47], v[148:151], v[214:217], v[44:47]
	v_mfma_f32_16x16x32_bf16 v[36:39], v[156:159], v[214:217], v[36:39]
	v_mfma_f32_16x16x32_bf16 v[28:31], v[148:151], v[222:225], v[28:31]
	v_mfma_f32_16x16x32_bf16 v[20:23], v[156:159], v[222:225], v[20:23]
	v_mfma_f32_16x16x32_bf16 v[40:43], v[168:171], v[184:187], v[40:43]
	v_mfma_f32_16x16x32_bf16 v[32:35], v[176:179], v[184:187], v[32:35]
	v_mfma_f32_16x16x32_bf16 v[24:27], v[168:171], v[192:195], v[24:27]
	v_mfma_f32_16x16x32_bf16 v[16:19], v[176:179], v[192:195], v[16:19]
	v_mfma_f32_16x16x32_bf16 v[12:15], v[168:171], v[210:213], v[12:15]
	v_mfma_f32_16x16x32_bf16 v[8:11], v[176:179], v[210:213], v[8:11]
	v_mfma_f32_16x16x32_bf16 v[4:7], v[168:171], v[218:221], v[4:7]
	v_mfma_f32_16x16x32_bf16 v[0:3], v[176:179], v[218:221], v[0:3]
	v_mfma_f32_16x16x32_bf16 v[40:43], v[172:175], v[188:191], v[40:43]
	v_mfma_f32_16x16x32_bf16 v[32:35], v[180:183], v[188:191], v[32:35]
	v_mfma_f32_16x16x32_bf16 v[24:27], v[172:175], v[196:199], v[24:27]
	v_mfma_f32_16x16x32_bf16 v[16:19], v[180:183], v[196:199], v[16:19]
	v_mfma_f32_16x16x32_bf16 v[12:15], v[172:175], v[214:217], v[12:15]
	v_mfma_f32_16x16x32_bf16 v[8:11], v[180:183], v[214:217], v[8:11]
	v_mfma_f32_16x16x32_bf16 v[4:7], v[172:175], v[222:225], v[4:7]
	v_mfma_f32_16x16x32_bf16 v[0:3], v[180:183], v[222:225], v[0:3]
	s_setprio 0
	s_barrier
	s_add_i32 s41, s41, 2
	s_add_u32 s13, s13, 0x100
	s_addc_u32 s40, s40, 0
	s_add_u32 s18, s18, 0x100
	s_addc_u32 s19, s19, 0
	s_cmp_gt_u32 s41, 29
	s_cbranch_scc0 .LBB0_285
	s_and_b64 vcc, exec, s[10:11]
	s_cbranch_vccz .LBB0_288
	s_barrier

; #define PG8_STAGE(bufoff, gbase, voff) do { _Pragma("unroll") for (int _i = 0; _i < 2; ++_i) \
;         __builtin_amdgcn_global_load_lds((const unsigned*)((const char*)(gbase) + (voff)[_i]), (LAS unsigned*)(lds + (bufoff) + ldsw + _i * 8192), 16, 0, 0); } while (0)
; #define PG8_LDA(dst, b, h) do { _Pragma("unroll") for (int m = 0; m < 4; ++m) _Pragma("unroll") for (int k = 0; k < 2; ++k) dst[m][k] = *(const LAS bf16x8*)(lds + PG8_SA(b, h) + aoff + m * 2048 + k * 1024); } while (0)
; #define PG8_LDB(dst, b, h) do { _Pragma("unroll") for (int n = 0; n < 2; ++n) _Pragma("unroll") for (int k = 0; k < 2; ++k) dst[n][k] = *(const LAS bf16x8*)(lds + PG8_SB(b, h) + boff + n * 2048 + k * 1024); } while (0)
; #define PG8_MMA(ai, bj, At, Bt) do { __builtin_amdgcn_s_setprio(1); _Pragma("unroll") for (int m = 0; m < 4; ++m) _Pragma("unroll") for (int n = 0; n < 2; ++n) _Pragma("unroll") for (int k = 0; k < 2; ++k) \
;         acc[ai][bj][m][n] = __builtin_amdgcn_mfma_f32_16x16x32_bf16(Bt[n][k], At[m][k], acc[ai][bj][m][n], 0, 0, 0); __builtin_amdgcn_s_setprio(0); } while (0)
; #define PG8_WAIT_V(n) asm volatile("s_waitcnt vmcnt(" #n ")" ::: "memory")
; #define PG8_WAIT_L(n) asm volatile("s_waitcnt lgkmcnt(" #n ")" ::: "memory")
; #define PG8_BAR __builtin_amdgcn_s_barrier()
; #define PG8_SCHED __builtin_amdgcn_sched_barrier(0)
; template <class Epi, class Sched>
; DI void gemm_phase(const int wv, LAS unsigned char* lds, const int lda, const int ldb, const int K, const Sched& S, const Epi& E) {
;     ...
;             const bool last = (t == nt - 2);
;             const char* a1 = cA + (size_t)(t + 1) * kstep;
;             const char* a2 = last ? nA : cA + (size_t)(t + 2) * kstep; const char* b2 = last ? nB : cB + (size_t)(t + 2) * kstep;
;             const char* a3 = a2 + kstep; const char* b3 = b2 + kstep;
;             PG8_LDB(B0, 0, 0); PG8_LDB(B1, 0, 1); PG8_SCHED; PG8_LDA(At, 0, 0); PG8_STAGE(PG8_SA(1, 1), a1 + hstepA, voffA);
;             PG8_WAIT_V(8); PG8_WAIT_L(0); PG8_BAR; PG8_MMA(0, 0, At, B0); PG8_MMA(0, 1, At, B1); PG8_BAR; PG8_SCHED;
;             PG8_LDA(At, 0, 1); PG8_STAGE(PG8_SB(0, 0), b2, voffB); PG8_STAGE(PG8_SB(0, 1), b2 + hstepB, voffB); PG8_STAGE(PG8_SA(0, 0), a2, voffA);
;             PG8_WAIT_V(8); PG8_WAIT_L(0); PG8_BAR; PG8_MMA(1, 0, At, B0); PG8_MMA(1, 1, At, B1); PG8_BAR; PG8_SCHED;
.LBB0_516:
	s_add_u32 s14, s2, s8
	s_addc_u32 s15, s3, s9
	s_add_u32 s12, s14, 0x100
	s_addc_u32 s13, s15, 0
	s_and_b64 s[10:11], s[6:7], exec
	s_cselect_b32 s11, s3, s13
	s_cselect_b32 s10, s2, s12
	s_add_u32 s8, s0, s8
	s_addc_u32 s9, s1, s9
	s_add_u32 s8, s8, 0x100
	s_addc_u32 s9, s9, 0
	s_add_i32 s39, 0, 0x10000
	s_and_b64 s[6:7], s[6:7], exec
	s_cselect_b32 s13, s1, s9
	s_cselect_b32 s12, s0, s8
	s_add_i32 s7, 0, 0x14000
	s_add_u32 s16, s14, 0x40080
	s_addc_u32 s17, s15, 0
	s_add_i32 s38, s39, s21
	s_add_i32 m0, s22, 0xc000
	s_add_i32 s41, s22, 0xe000
	s_add_i32 s35, s38, 0x2000
	s_add_u32 s14, s12, 0x10000
	v_add_u32_e32 v150, s39, v136
	v_add_u32_e32 v158, s7, v136
	s_addc_u32 s15, s13, 0
	s_add_i32 s37, s7, s21
	ds_read_b128 v[138:141], v150
	ds_read_b128 v[142:145], v150 offset:1024
	ds_read_b128 v[146:149], v150 offset:2048
	ds_read_b128 v[150:153], v150 offset:3072
	ds_read_b128 v[154:157], v158
	ds_read_b128 v[162:165], v158 offset:1024
	ds_read_b128 v[168:171], v158 offset:2048
	ds_read_b128 v[172:175], v158 offset:3072
	s_add_i32 s36, s37, 0x2000
	s_add_i32 s34, 0, 0x18000
	s_add_i32 s31, 0, 0x1c000
	s_add_u32 s8, s10, 0x40000
	s_addc_u32 s9, s11, 0
	s_add_i32 s30, s34, s21
	s_add_i32 s29, s30, 0x2000
	s_add_u32 s6, s12, 0x10080
	s_addc_u32 s7, s13, 0
	s_add_i32 s40, s31, s21
	s_add_i32 s39, s40, 0x2000
	v_lshl_add_u64 v[158:159], s[16:17], 0, v[128:129]
	ds_read_b128 v[176:179], v137
	ds_read_b128 v[180:183], v137 offset:1024
	ds_read_b128 v[184:187], v137 offset:2048
	ds_read_b128 v[188:191], v137 offset:3072
	ds_read_b128 v[192:195], v137 offset:4096
	ds_read_b128 v[196:199], v137 offset:5120
	ds_read_b128 v[210:213], v137 offset:6144
	ds_read_b128 v[214:217], v137 offset:7168
	global_load_lds_dwordx4 v[158:159], off
	v_lshl_add_u64 v[158:159], s[16:17], 0, v[130:131]
	s_mov_b32 m0, s41
	s_nop 0
	global_load_lds_dwordx4 v[158:159], off
	s_waitcnt vmcnt(8) lgkmcnt(0)
	s_barrier
	s_setprio 1
	v_mfma_f32_16x16x32_bf16 v[124:127], v[138:141], v[176:179], v[124:127]
	v_mfma_f32_16x16x32_bf16 v[120:123], v[146:149], v[176:179], v[120:123]
	v_mfma_f32_16x16x32_bf16 v[116:119], v[138:141], v[184:187], v[116:119]
	v_mfma_f32_16x16x32_bf16 v[112:115], v[146:149], v[184:187], v[112:115]
	v_mfma_f32_16x16x32_bf16 v[100:103], v[138:141], v[192:195], v[100:103]
	v_mfma_f32_16x16x32_bf16 v[96:99], v[146:149], v[192:195], v[96:99]
	v_mfma_f32_16x16x32_bf16 v[84:87], v[138:141], v[210:213], v[84:87]
	v_mfma_f32_16x16x32_bf16 v[80:83], v[146:149], v[210:213], v[80:83]
	v_mfma_f32_16x16x32_bf16 v[124:127], v[142:145], v[180:183], v[124:127]
	v_mfma_f32_16x16x32_bf16 v[120:123], v[150:153], v[180:183], v[120:123]
	v_mfma_f32_16x16x32_bf16 v[116:119], v[142:145], v[188:191], v[116:119]
	v_mfma_f32_16x16x32_bf16 v[112:115], v[150:153], v[188:191], v[112:115]
	v_mfma_f32_16x16x32_bf16 v[100:103], v[142:145], v[196:199], v[100:103]
	v_mfma_f32_16x16x32_bf16 v[96:99], v[150:153], v[196:199], v[96:99]
	v_mfma_f32_16x16x32_bf16 v[84:87], v[142:145], v[214:217], v[84:87]
	v_mfma_f32_16x16x32_bf16 v[80:83], v[150:153], v[214:217], v[80:83]
	v_mfma_f32_16x16x32_bf16 v[108:111], v[154:157], v[176:179], v[108:111]
	v_mfma_f32_16x16x32_bf16 v[104:107], v[168:171], v[176:179], v[104:107]
	v_mfma_f32_16x16x32_bf16 v[92:95], v[154:157], v[184:187], v[92:95]
	v_mfma_f32_16x16x32_bf16 v[88:91], v[168:171], v[184:187], v[88:91]
	v_mfma_f32_16x16x32_bf16 v[76:79], v[154:157], v[192:195], v[76:79]
	v_mfma_f32_16x16x32_bf16 v[72:75], v[168:171], v[192:195], v[72:75]
	v_mfma_f32_16x16x32_bf16 v[68:71], v[154:157], v[210:213], v[68:71]
	v_mfma_f32_16x16x32_bf16 v[64:67], v[168:171], v[210:213], v[64:67]
	v_mfma_f32_16x16x32_bf16 v[108:111], v[162:165], v[180:183], v[108:111]
	v_mfma_f32_16x16x32_bf16 v[104:107], v[172:175], v[180:183], v[104:107]
	v_mfma_f32_16x16x32_bf16 v[92:95], v[162:165], v[188:191], v[92:95]
	v_mfma_f32_16x16x32_bf16 v[88:91], v[172:175], v[188:191], v[88:91]
	v_mfma_f32_16x16x32_bf16 v[76:79], v[162:165], v[196:199], v[76:79]
	v_mfma_f32_16x16x32_bf16 v[72:75], v[172:175], v[196:199], v[72:75]
	v_mfma_f32_16x16x32_bf16 v[68:71], v[162:165], v[214:217], v[68:71]
	v_mfma_f32_16x16x32_bf16 v[64:67], v[172:175], v[214:217], v[64:67]
	s_setprio 0
	s_barrier
	s_mov_b32 m0, s38
	v_lshl_add_u64 v[158:159], s[12:13], 0, v[160:161]
	ds_read_b128 v[176:179], v137 offset:16384
	ds_read_b128 v[180:183], v137 offset:17408
	ds_read_b128 v[184:187], v137 offset:18432
	ds_read_b128 v[188:191], v137 offset:19456
	ds_read_b128 v[192:195], v137 offset:20480
	ds_read_b128 v[196:199], v137 offset:21504
	ds_read_b128 v[210:213], v137 offset:22528
	ds_read_b128 v[214:217], v137 offset:23552
	global_load_lds_dwordx4 v[158:159], off
	v_lshl_add_u64 v[218:219], s[12:13], 0, v[132:133]
	s_mov_b32 m0, s35
	v_lshl_add_u64 v[220:221], s[14:15], 0, v[160:161]
	global_load_lds_dwordx4 v[218:219], off
	s_mov_b32 m0, s37
	v_lshl_add_u64 v[222:223], s[10:11], 0, v[130:131]
	global_load_lds_dwordx4 v[220:221], off
	v_lshl_add_u64 v[220:221], s[14:15], 0, v[132:133]
	s_mov_b32 m0, s36
	s_nop 0
	global_load_lds_dwordx4 v[220:221], off
	v_lshl_add_u64 v[220:221], s[10:11], 0, v[128:129]
	s_mov_b32 m0, s22
	s_nop 0
	global_load_lds_dwordx4 v[220:221], off
	s_mov_b32 m0, s23
	s_nop 0
	global_load_lds_dwordx4 v[222:223], off
	s_waitcnt vmcnt(8) lgkmcnt(0)
	s_barrier
; #define PG8_STAGE(bufoff, gbase, voff) do { _Pragma("unroll") for (int _i = 0; _i < 2; ++_i) \
;         __builtin_amdgcn_global_load_lds((const unsigned*)((const char*)(gbase) + (voff)[_i]), (LAS unsigned*)(lds + (bufoff) + ldsw + _i * 8192), 16, 0, 0); } while (0)
; #define PG8_LDA(dst, b, h) do { _Pragma("unroll") for (int m = 0; m < 4; ++m) _Pragma("unroll") for (int k = 0; k < 2; ++k) dst[m][k] = *(const LAS bf16x8*)(lds + PG8_SA(b, h) + aoff + m * 2048 + k * 1024); } while (0)
; #define PG8_LDB(dst, b, h) do { _Pragma("unroll") for (int n = 0; n < 2; ++n) _Pragma("unroll") for (int k = 0; k < 2; ++k) dst[n][k] = *(const LAS bf16x8*)(lds + PG8_SB(b, h) + boff + n * 2048 + k * 1024); } while (0)
; #define PG8_MMA(ai, bj, At, Bt) do { __builtin_amdgcn_s_setprio(1); _Pragma("unroll") for (int m = 0; m < 4; ++m) _Pragma("unroll") for (int n = 0; n < 2; ++n) _Pragma("unroll") for (int k = 0; k < 2; ++k) \
;         acc[ai][bj][m][n] = __builtin_amdgcn_mfma_f32_16x16x32_bf16(Bt[n][k], At[m][k], acc[ai][bj][m][n], 0, 0, 0); __builtin_amdgcn_s_setprio(0); } while (0)
; #define PG8_WAIT_V(n) asm volatile("s_waitcnt vmcnt(" #n ")" ::: "memory")
; #define PG8_WAIT_L(n) asm volatile("s_waitcnt lgkmcnt(" #n ")" ::: "memory")
; #define PG8_BAR __builtin_amdgcn_s_barrier()
; #define PG8_SCHED __builtin_amdgcn_sched_barrier(0)
; template <class Epi, class Sched>
; DI void gemm_phase(const int wv, LAS unsigned char* lds, const int lda, const int ldb, const int K, const Sched& S, const Epi& E) {
;     ...
;             PG8_WAIT_V(8); PG8_WAIT_L(0); PG8_BAR; PG8_MMA(1, 0, At, B0); PG8_MMA(1, 1, At, B1); PG8_BAR; PG8_SCHED;
;             PG8_LDB(B0, 1, 0); PG8_LDB(B1, 1, 1); PG8_SCHED; PG8_LDA(At, 1, 0); PG8_STAGE(PG8_SA(0, 1), a2 + hstepA, voffA);
;             PG8_WAIT_V(8); PG8_WAIT_L(0); PG8_BAR; PG8_MMA(0, 0, At, B0); PG8_MMA(0, 1, At, B1); PG8_BAR; PG8_SCHED;
	s_setprio 1
	v_mfma_f32_16x16x32_bf16 v[60:63], v[138:141], v[176:179], v[60:63]
	v_mfma_f32_16x16x32_bf16 v[56:59], v[146:149], v[176:179], v[56:59]
	v_mfma_f32_16x16x32_bf16 v[52:55], v[138:141], v[184:187], v[52:55]
	v_mfma_f32_16x16x32_bf16 v[48:51], v[146:149], v[184:187], v[48:51]
	v_mfma_f32_16x16x32_bf16 v[36:39], v[138:141], v[192:195], v[36:39]
	v_mfma_f32_16x16x32_bf16 v[32:35], v[146:149], v[192:195], v[32:35]
	v_mfma_f32_16x16x32_bf16 v[20:23], v[138:141], v[210:213], v[20:23]
	v_mfma_f32_16x16x32_bf16 v[16:19], v[146:149], v[210:213], v[16:19]
	v_mfma_f32_16x16x32_bf16 v[60:63], v[142:145], v[180:183], v[60:63]
	v_mfma_f32_16x16x32_bf16 v[56:59], v[150:153], v[180:183], v[56:59]
	v_mfma_f32_16x16x32_bf16 v[52:55], v[142:145], v[188:191], v[52:55]
	v_mfma_f32_16x16x32_bf16 v[48:51], v[150:153], v[188:191], v[48:51]
	v_mfma_f32_16x16x32_bf16 v[36:39], v[142:145], v[196:199], v[36:39]
	v_mfma_f32_16x16x32_bf16 v[32:35], v[150:153], v[196:199], v[32:35]
	v_mfma_f32_16x16x32_bf16 v[20:23], v[142:145], v[214:217], v[20:23]
	v_mfma_f32_16x16x32_bf16 v[16:19], v[150:153], v[214:217], v[16:19]
	v_mfma_f32_16x16x32_bf16 v[44:47], v[154:157], v[176:179], v[44:47]
	v_mfma_f32_16x16x32_bf16 v[40:43], v[168:171], v[176:179], v[40:43]
	v_mfma_f32_16x16x32_bf16 v[28:31], v[154:157], v[184:187], v[28:31]
	v_mfma_f32_16x16x32_bf16 v[24:27], v[168:171], v[184:187], v[24:27]
	v_mfma_f32_16x16x32_bf16 v[12:15], v[154:157], v[192:195], v[12:15]
	v_mfma_f32_16x16x32_bf16 v[8:11], v[168:171], v[192:195], v[8:11]
	v_mfma_f32_16x16x32_bf16 v[4:7], v[154:157], v[210:213], v[4:7]
	v_mfma_f32_16x16x32_bf16 v[0:3], v[168:171], v[210:213], v[0:3]
	v_mfma_f32_16x16x32_bf16 v[44:47], v[162:165], v[180:183], v[44:47]
	v_mfma_f32_16x16x32_bf16 v[40:43], v[172:175], v[180:183], v[40:43]
	v_mfma_f32_16x16x32_bf16 v[28:31], v[162:165], v[188:191], v[28:31]
	v_mfma_f32_16x16x32_bf16 v[24:27], v[172:175], v[188:191], v[24:27]
	v_mfma_f32_16x16x32_bf16 v[12:15], v[162:165], v[196:199], v[12:15]
	v_mfma_f32_16x16x32_bf16 v[8:11], v[172:175], v[196:199], v[8:11]
	v_mfma_f32_16x16x32_bf16 v[4:7], v[162:165], v[214:217], v[4:7]
	v_mfma_f32_16x16x32_bf16 v[0:3], v[172:175], v[214:217], v[0:3]
	s_setprio 0
	s_barrier
	v_add_u32_e32 v150, s34, v136
	v_add_u32_e32 v172, s31, v136
	ds_read_b128 v[138:141], v150
	ds_read_b128 v[142:145], v150 offset:1024
	ds_read_b128 v[146:149], v150 offset:2048
	ds_read_b128 v[150:153], v150 offset:3072
	ds_read_b128 v[154:157], v172
	ds_read_b128 v[162:165], v172 offset:1024
	ds_read_b128 v[168:171], v172 offset:2048
	ds_read_b128 v[172:175], v172 offset:3072
	s_mov_b32 m0, s24
	v_lshl_add_u64 v[224:225], s[8:9], 0, v[128:129]
	ds_read_b128 v[176:179], v137 offset:32768
	ds_read_b128 v[180:183], v137 offset:33792
	ds_read_b128 v[184:187], v137 offset:34816
	ds_read_b128 v[188:191], v137 offset:35840
	ds_read_b128 v[192:195], v137 offset:36864
	ds_read_b128 v[196:199], v137 offset:37888
	ds_read_b128 v[210:213], v137 offset:38912
	ds_read_b128 v[214:217], v137 offset:39936
	global_load_lds_dwordx4 v[224:225], off
	v_lshl_add_u64 v[224:225], s[8:9], 0, v[130:131]
	s_mov_b32 m0, s25
	s_nop 0
	global_load_lds_dwordx4 v[224:225], off
	s_waitcnt vmcnt(8) lgkmcnt(0)
	s_barrier
	s_setprio 1
	v_mfma_f32_16x16x32_bf16 v[124:127], v[138:141], v[176:179], v[124:127]
	v_mfma_f32_16x16x32_bf16 v[120:123], v[146:149], v[176:179], v[120:123]
	v_mfma_f32_16x16x32_bf16 v[116:119], v[138:141], v[184:187], v[116:119]
	v_mfma_f32_16x16x32_bf16 v[112:115], v[146:149], v[184:187], v[112:115]
	v_mfma_f32_16x16x32_bf16 v[100:103], v[138:141], v[192:195], v[100:103]
	v_mfma_f32_16x16x32_bf16 v[96:99], v[146:149], v[192:195], v[96:99]
	v_mfma_f32_16x16x32_bf16 v[84:87], v[138:141], v[210:213], v[84:87]
	v_mfma_f32_16x16x32_bf16 v[80:83], v[146:149], v[210:213], v[80:83]
	v_mfma_f32_16x16x32_bf16 v[124:127], v[142:145], v[180:183], v[124:127]
	v_mfma_f32_16x16x32_bf16 v[120:123], v[150:153], v[180:183], v[120:123]
	v_mfma_f32_16x16x32_bf16 v[116:119], v[142:145], v[188:191], v[116:119]
	v_mfma_f32_16x16x32_bf16 v[112:115], v[150:153], v[188:191], v[112:115]
	v_mfma_f32_16x16x32_bf16 v[100:103], v[142:145], v[196:199], v[100:103]
	v_mfma_f32_16x16x32_bf16 v[96:99], v[150:153], v[196:199], v[96:99]
	v_mfma_f32_16x16x32_bf16 v[84:87], v[142:145], v[214:217], v[84:87]
	v_mfma_f32_16x16x32_bf16 v[80:83], v[150:153], v[214:217], v[80:83]
	v_mfma_f32_16x16x32_bf16 v[108:111], v[154:157], v[176:179], v[108:111]
	v_mfma_f32_16x16x32_bf16 v[104:107], v[168:171], v[176:179], v[104:107]
	v_mfma_f32_16x16x32_bf16 v[92:95], v[154:157], v[184:187], v[92:95]
	v_mfma_f32_16x16x32_bf16 v[88:91], v[168:171], v[184:187], v[88:91]
	v_mfma_f32_16x16x32_bf16 v[76:79], v[154:157], v[192:195], v[76:79]
	v_mfma_f32_16x16x32_bf16 v[72:75], v[168:171], v[192:195], v[72:75]
	v_mfma_f32_16x16x32_bf16 v[68:71], v[154:157], v[210:213], v[68:71]
	v_mfma_f32_16x16x32_bf16 v[64:67], v[168:171], v[210:213], v[64:67]
	v_mfma_f32_16x16x32_bf16 v[108:111], v[162:165], v[180:183], v[108:111]
	v_mfma_f32_16x16x32_bf16 v[104:107], v[172:175], v[180:183], v[104:107]
	v_mfma_f32_16x16x32_bf16 v[92:95], v[162:165], v[188:191], v[92:95]
	v_mfma_f32_16x16x32_bf16 v[88:91], v[172:175], v[188:191], v[88:91]
	v_mfma_f32_16x16x32_bf16 v[76:79], v[162:165], v[196:199], v[76:79]
	v_mfma_f32_16x16x32_bf16 v[72:75], v[172:175], v[196:199], v[72:75]
	v_mfma_f32_16x16x32_bf16 v[68:71], v[162:165], v[214:217], v[68:71]
	v_mfma_f32_16x16x32_bf16 v[64:67], v[172:175], v[214:217], v[64:67]
	s_setprio 0
	s_barrier
; #define PG8_STAGE(bufoff, gbase, voff) do { _Pragma("unroll") for (int _i = 0; _i < 2; ++_i) \
;         __builtin_amdgcn_global_load_lds((const unsigned*)((const char*)(gbase) + (voff)[_i]), (LAS unsigned*)(lds + (bufoff) + ldsw + _i * 8192), 16, 0, 0); } while (0)
; #define PG8_LDA(dst, b, h) do { _Pragma("unroll") for (int m = 0; m < 4; ++m) _Pragma("unroll") for (int k = 0; k < 2; ++k) dst[m][k] = *(const LAS bf16x8*)(lds + PG8_SA(b, h) + aoff + m * 2048 + k * 1024); } while (0)
; #define PG8_MMA(ai, bj, At, Bt) do { __builtin_amdgcn_s_setprio(1); _Pragma("unroll") for (int m = 0; m < 4; ++m) _Pragma("unroll") for (int n = 0; n < 2; ++n) _Pragma("unroll") for (int k = 0; k < 2; ++k) \
;         acc[ai][bj][m][n] = __builtin_amdgcn_mfma_f32_16x16x32_bf16(Bt[n][k], At[m][k], acc[ai][bj][m][n], 0, 0, 0); __builtin_amdgcn_s_setprio(0); } while (0)
; #define PG8_WAIT_V(n) asm volatile("s_waitcnt vmcnt(" #n ")" ::: "memory")
; #define PG8_WAIT_L(n) asm volatile("s_waitcnt lgkmcnt(" #n ")" ::: "memory")
; #define PG8_BAR __builtin_amdgcn_s_barrier()
; #define PG8_SCHED __builtin_amdgcn_sched_barrier(0)
; template <class Epi, class Sched>
; DI void gemm_phase(const int wv, LAS unsigned char* lds, const int lda, const int ldb, const int K, const Sched& S, const Epi& E) {
;     ...
;             PG8_LDA(At, 1, 1); PG8_STAGE(PG8_SB(1, 0), b3, voffB); PG8_STAGE(PG8_SB(1, 1), b3 + hstepB, voffB); PG8_STAGE(PG8_SA(1, 0), a3, voffA);
;             PG8_WAIT_V(8); PG8_WAIT_L(0); PG8_BAR; PG8_MMA(1, 0, At, B0); PG8_MMA(1, 1, At, B1); PG8_BAR; PG8_SCHED;
;         }
;         if (wr == 0) PG8_BAR;
	s_mov_b32 m0, s30
	v_lshl_add_u64 v[158:159], v[158:159], 0, s[78:79]
	ds_read_b128 v[176:179], v137 offset:49152
	ds_read_b128 v[180:183], v137 offset:50176
	ds_read_b128 v[184:187], v137 offset:51200
	ds_read_b128 v[188:191], v137 offset:52224
	ds_read_b128 v[192:195], v137 offset:53248
	ds_read_b128 v[196:199], v137 offset:54272
	ds_read_b128 v[210:213], v137 offset:55296
	ds_read_b128 v[214:217], v137 offset:56320
	global_load_lds_dwordx4 v[158:159], off
	v_lshl_add_u64 v[158:159], v[218:219], 0, s[78:79]
	s_mov_b32 m0, s29
	s_nop 0
	global_load_lds_dwordx4 v[158:159], off
	v_lshl_add_u64 v[158:159], s[6:7], 0, v[160:161]
	s_mov_b32 m0, s40
	s_nop 0
	global_load_lds_dwordx4 v[158:159], off
	v_lshl_add_u64 v[158:159], s[6:7], 0, v[132:133]
	s_mov_b32 m0, s39
	s_nop 0
	global_load_lds_dwordx4 v[158:159], off
	v_lshl_add_u64 v[158:159], v[220:221], 0, s[78:79]
	s_mov_b32 m0, s27
	s_nop 0
	global_load_lds_dwordx4 v[158:159], off
	v_lshl_add_u64 v[158:159], v[222:223], 0, s[78:79]
	s_mov_b32 m0, s28
	s_nop 0
	global_load_lds_dwordx4 v[158:159], off
	s_waitcnt vmcnt(8) lgkmcnt(0)
	s_barrier
	s_setprio 1
	v_mfma_f32_16x16x32_bf16 v[60:63], v[138:141], v[176:179], v[60:63]
	v_mfma_f32_16x16x32_bf16 v[56:59], v[146:149], v[176:179], v[56:59]
	v_mfma_f32_16x16x32_bf16 v[52:55], v[138:141], v[184:187], v[52:55]
	v_mfma_f32_16x16x32_bf16 v[48:51], v[146:149], v[184:187], v[48:51]
	v_mfma_f32_16x16x32_bf16 v[36:39], v[138:141], v[192:195], v[36:39]
	v_mfma_f32_16x16x32_bf16 v[32:35], v[146:149], v[192:195], v[32:35]
	v_mfma_f32_16x16x32_bf16 v[20:23], v[138:141], v[210:213], v[20:23]
	v_mfma_f32_16x16x32_bf16 v[16:19], v[146:149], v[210:213], v[16:19]
	v_mfma_f32_16x16x32_bf16 v[60:63], v[142:145], v[180:183], v[60:63]
	v_mfma_f32_16x16x32_bf16 v[56:59], v[150:153], v[180:183], v[56:59]
	v_mfma_f32_16x16x32_bf16 v[52:55], v[142:145], v[188:191], v[52:55]
	v_mfma_f32_16x16x32_bf16 v[48:51], v[150:153], v[188:191], v[48:51]
	v_mfma_f32_16x16x32_bf16 v[36:39], v[142:145], v[196:199], v[36:39]
	v_mfma_f32_16x16x32_bf16 v[32:35], v[150:153], v[196:199], v[32:35]
	v_mfma_f32_16x16x32_bf16 v[20:23], v[142:145], v[214:217], v[20:23]
	v_mfma_f32_16x16x32_bf16 v[16:19], v[150:153], v[214:217], v[16:19]
	v_mfma_f32_16x16x32_bf16 v[44:47], v[154:157], v[176:179], v[44:47]
	v_mfma_f32_16x16x32_bf16 v[40:43], v[168:171], v[176:179], v[40:43]
	v_mfma_f32_16x16x32_bf16 v[28:31], v[154:157], v[184:187], v[28:31]
	v_mfma_f32_16x16x32_bf16 v[24:27], v[168:171], v[184:187], v[24:27]
	v_mfma_f32_16x16x32_bf16 v[12:15], v[154:157], v[192:195], v[12:15]
	v_mfma_f32_16x16x32_bf16 v[8:11], v[168:171], v[192:195], v[8:11]
	v_mfma_f32_16x16x32_bf16 v[4:7], v[154:157], v[210:213], v[4:7]
	v_mfma_f32_16x16x32_bf16 v[0:3], v[168:171], v[210:213], v[0:3]
	v_mfma_f32_16x16x32_bf16 v[44:47], v[162:165], v[180:183], v[44:47]
	v_mfma_f32_16x16x32_bf16 v[40:43], v[172:175], v[180:183], v[40:43]
	v_mfma_f32_16x16x32_bf16 v[28:31], v[162:165], v[188:191], v[28:31]
	v_mfma_f32_16x16x32_bf16 v[24:27], v[172:175], v[188:191], v[24:27]
	v_mfma_f32_16x16x32_bf16 v[12:15], v[162:165], v[196:199], v[12:15]
	v_mfma_f32_16x16x32_bf16 v[8:11], v[172:175], v[196:199], v[8:11]
	v_mfma_f32_16x16x32_bf16 v[4:7], v[162:165], v[214:217], v[4:7]
	v_mfma_f32_16x16x32_bf16 v[0:3], v[172:175], v[214:217], v[0:3]
	s_setprio 0
	s_barrier
	s_andn2_b64 vcc, exec, s[4:5]
	s_mov_b64 s[6:7], -1
	s_mov_b64 s[4:5], 0
	s_mov_b64 s[8:9], 0x100
	s_cbranch_vccz .LBB0_516
	s_cmpk_lt_u32 s20, 0x100
	s_cbranch_scc0 .LBB0_519
	s_barrier

; #define PG8_STAGE(bufoff, gbase, voff) do { _Pragma("unroll") for (int _i = 0; _i < 2; ++_i) \
;         __builtin_amdgcn_global_load_lds((const unsigned*)((const char*)(gbase) + (voff)[_i]), (LAS unsigned*)(lds + (bufoff) + ldsw + _i * 8192), 16, 0, 0); } while (0)
; #define PG8_LDA(dst, b, h) do { _Pragma("unroll") for (int m = 0; m < 4; ++m) _Pragma("unroll") for (int k = 0; k < 2; ++k) dst[m][k] = *(const LAS bf16x8*)(lds + PG8_SA(b, h) + aoff + m * 2048 + k * 1024); } while (0)
; #define PG8_LDB(dst, b, h) do { _Pragma("unroll") for (int n = 0; n < 2; ++n) _Pragma("unroll") for (int k = 0; k < 2; ++k) dst[n][k] = *(const LAS bf16x8*)(lds + PG8_SB(b, h) + boff + n * 2048 + k * 1024); } while (0)
; #define PG8_MMA(ai, bj, At, Bt) do { __builtin_amdgcn_s_setprio(1); _Pragma("unroll") for (int m = 0; m < 4; ++m) _Pragma("unroll") for (int n = 0; n < 2; ++n) _Pragma("unroll") for (int k = 0; k < 2; ++k) \
;         acc[ai][bj][m][n] = __builtin_amdgcn_mfma_f32_16x16x32_bf16(Bt[n][k], At[m][k], acc[ai][bj][m][n], 0, 0, 0); __builtin_amdgcn_s_setprio(0); } while (0)
; #define PG8_WAIT_V(n) asm volatile("s_waitcnt vmcnt(" #n ")" ::: "memory")
; #define PG8_WAIT_L(n) asm volatile("s_waitcnt lgkmcnt(" #n ")" ::: "memory")
; #define PG8_BAR __builtin_amdgcn_s_barrier()
; #define PG8_SCHED __builtin_amdgcn_sched_barrier(0)
; template <class Epi, class Sched>
; DI void gemm_phase(const int wv, LAS unsigned char* lds, const int lda, const int ldb, const int K, const Sched& S, const Epi& E) {
;     ...
;             const bool last = (t == nt - 2);
;             const char* a1 = cA + (size_t)(t + 1) * kstep;
;             const char* a2 = last ? nA : cA + (size_t)(t + 2) * kstep; const char* b2 = last ? nB : cB + (size_t)(t + 2) * kstep;
;             const char* a3 = a2 + kstep; const char* b3 = b2 + kstep;
;             PG8_LDB(B0, 0, 0); PG8_LDB(B1, 0, 1); PG8_SCHED; PG8_LDA(At, 0, 0); PG8_STAGE(PG8_SA(1, 1), a1 + hstepA, voffA);
;             PG8_WAIT_V(8); PG8_WAIT_L(0); PG8_BAR; PG8_MMA(0, 0, At, B0); PG8_MMA(0, 1, At, B1); PG8_BAR; PG8_SCHED;
;             PG8_LDA(At, 0, 1); PG8_STAGE(PG8_SB(0, 0), b2, voffB); PG8_STAGE(PG8_SB(0, 1), b2 + hstepB, voffB); PG8_STAGE(PG8_SA(0, 0), a2, voffA);
;             PG8_WAIT_V(8); PG8_WAIT_L(0); PG8_BAR; PG8_MMA(1, 0, At, B0); PG8_MMA(1, 1, At, B1); PG8_BAR; PG8_SCHED;
.LBB0_686:
	s_add_u32 s18, s16, 0xfff80080
	s_addc_u32 s19, s17, -1
	s_add_i32 s42, 0, 0x10000
	s_cmp_eq_u32 s41, 28
	s_cselect_b32 s21, s13, s19
	s_cselect_b32 s20, s12, s18
	s_cselect_b32 s19, s15, s40
	s_cselect_b32 s18, s14, s11
	s_add_i32 s44, 0, 0x14000
	v_add_u32_e32 v140, s42, v157
	v_add_u32_e32 v154, s44, v157
	ds_read_b128 v[128:131], v140
	ds_read_b128 v[132:135], v140 offset:1024
	ds_read_b128 v[136:139], v140 offset:2048
	ds_read_b128 v[140:143], v140 offset:3072
	ds_read_b128 v[162:165], v154
	ds_read_b128 v[168:171], v154 offset:1024
	ds_read_b128 v[172:175], v154 offset:2048
	ds_read_b128 v[176:179], v154 offset:3072
	v_lshl_add_u64 v[154:155], s[16:17], 0, v[152:153]
	s_add_i32 m0, s27, 0xc000
	ds_read_b128 v[180:183], v159
	ds_read_b128 v[184:187], v159 offset:1024
	ds_read_b128 v[188:191], v159 offset:2048
	ds_read_b128 v[192:195], v159 offset:3072
	ds_read_b128 v[196:199], v159 offset:4096
	ds_read_b128 v[210:213], v159 offset:5120
	ds_read_b128 v[214:217], v159 offset:6144
	ds_read_b128 v[218:221], v159 offset:7168
	global_load_lds_dwordx4 v[154:155], off
	v_lshl_add_u64 v[154:155], s[16:17], 0, v[150:151]
	s_add_i32 m0, s27, 0xe000
	s_nop 0
	global_load_lds_dwordx4 v[154:155], off
	s_waitcnt vmcnt(8) lgkmcnt(0)
	s_barrier
	s_setprio 1
	v_mfma_f32_16x16x32_bf16 v[124:127], v[128:131], v[180:183], v[124:127]
	v_mfma_f32_16x16x32_bf16 v[120:123], v[136:139], v[180:183], v[120:123]
	v_mfma_f32_16x16x32_bf16 v[116:119], v[128:131], v[188:191], v[116:119]
	v_mfma_f32_16x16x32_bf16 v[108:111], v[136:139], v[188:191], v[108:111]
	v_mfma_f32_16x16x32_bf16 v[100:103], v[128:131], v[196:199], v[100:103]
	v_mfma_f32_16x16x32_bf16 v[92:95], v[136:139], v[196:199], v[92:95]
	v_mfma_f32_16x16x32_bf16 v[84:87], v[128:131], v[214:217], v[84:87]
	v_mfma_f32_16x16x32_bf16 v[76:79], v[136:139], v[214:217], v[76:79]
	v_mfma_f32_16x16x32_bf16 v[124:127], v[132:135], v[184:187], v[124:127]
	v_mfma_f32_16x16x32_bf16 v[120:123], v[140:143], v[184:187], v[120:123]
	v_mfma_f32_16x16x32_bf16 v[116:119], v[132:135], v[192:195], v[116:119]
	v_mfma_f32_16x16x32_bf16 v[108:111], v[140:143], v[192:195], v[108:111]
	v_mfma_f32_16x16x32_bf16 v[100:103], v[132:135], v[210:213], v[100:103]
	v_mfma_f32_16x16x32_bf16 v[92:95], v[140:143], v[210:213], v[92:95]
	v_mfma_f32_16x16x32_bf16 v[84:87], v[132:135], v[218:221], v[84:87]
	v_mfma_f32_16x16x32_bf16 v[76:79], v[140:143], v[218:221], v[76:79]
	v_mfma_f32_16x16x32_bf16 v[112:115], v[162:165], v[180:183], v[112:115]
	v_mfma_f32_16x16x32_bf16 v[104:107], v[172:175], v[180:183], v[104:107]
	v_mfma_f32_16x16x32_bf16 v[96:99], v[162:165], v[188:191], v[96:99]
	v_mfma_f32_16x16x32_bf16 v[88:91], v[172:175], v[188:191], v[88:91]
	v_mfma_f32_16x16x32_bf16 v[80:83], v[162:165], v[196:199], v[80:83]
	v_mfma_f32_16x16x32_bf16 v[72:75], v[172:175], v[196:199], v[72:75]
	v_mfma_f32_16x16x32_bf16 v[68:71], v[162:165], v[214:217], v[68:71]
	v_mfma_f32_16x16x32_bf16 v[64:67], v[172:175], v[214:217], v[64:67]
	v_mfma_f32_16x16x32_bf16 v[112:115], v[168:171], v[184:187], v[112:115]
	v_mfma_f32_16x16x32_bf16 v[104:107], v[176:179], v[184:187], v[104:107]
	v_mfma_f32_16x16x32_bf16 v[96:99], v[168:171], v[192:195], v[96:99]
	v_mfma_f32_16x16x32_bf16 v[88:91], v[176:179], v[192:195], v[88:91]
	v_mfma_f32_16x16x32_bf16 v[80:83], v[168:171], v[210:213], v[80:83]
	v_mfma_f32_16x16x32_bf16 v[72:75], v[176:179], v[210:213], v[72:75]
	v_mfma_f32_16x16x32_bf16 v[68:71], v[168:171], v[218:221], v[68:71]
	v_mfma_f32_16x16x32_bf16 v[64:67], v[176:179], v[218:221], v[64:67]
	s_setprio 0
	s_barrier
	s_add_i32 s42, s42, s26
	v_lshl_add_u64 v[154:155], s[18:19], 0, v[160:161]
	s_mov_b32 m0, s42
	ds_read_b128 v[180:183], v159 offset:16384
	ds_read_b128 v[184:187], v159 offset:17408
	ds_read_b128 v[188:191], v159 offset:18432
	ds_read_b128 v[192:195], v159 offset:19456
	ds_read_b128 v[196:199], v159 offset:20480
	ds_read_b128 v[210:213], v159 offset:21504
	ds_read_b128 v[214:217], v159 offset:22528
	ds_read_b128 v[218:221], v159 offset:23552
	global_load_lds_dwordx4 v[154:155], off
	s_add_i32 m0, s42, 0x2000
	s_add_u32 s42, s18, 0x80000
	v_lshl_add_u64 v[222:223], s[18:19], 0, v[144:145]
	s_addc_u32 s43, s19, 0
	s_add_i32 s44, s44, s26
	global_load_lds_dwordx4 v[222:223], off
	v_lshl_add_u64 v[224:225], s[42:43], 0, v[160:161]
	s_mov_b32 m0, s44
	v_lshl_add_u64 v[226:227], s[20:21], 0, v[146:147]
	global_load_lds_dwordx4 v[224:225], off
	v_lshl_add_u64 v[224:225], s[42:43], 0, v[144:145]
	s_add_i32 m0, s44, 0x2000
	s_nop 0
	global_load_lds_dwordx4 v[224:225], off
	v_lshl_add_u64 v[224:225], s[20:21], 0, v[148:149]
	s_mov_b32 m0, s27
	s_nop 0
	global_load_lds_dwordx4 v[224:225], off
	s_mov_b32 m0, s28
	s_nop 0
	global_load_lds_dwordx4 v[226:227], off
	s_waitcnt vmcnt(8) lgkmcnt(0)
	s_barrier
; #define PG8_STAGE(bufoff, gbase, voff) do { _Pragma("unroll") for (int _i = 0; _i < 2; ++_i) \
;         __builtin_amdgcn_global_load_lds((const unsigned*)((const char*)(gbase) + (voff)[_i]), (LAS unsigned*)(lds + (bufoff) + ldsw + _i * 8192), 16, 0, 0); } while (0)
; #define PG8_LDA(dst, b, h) do { _Pragma("unroll") for (int m = 0; m < 4; ++m) _Pragma("unroll") for (int k = 0; k < 2; ++k) dst[m][k] = *(const LAS bf16x8*)(lds + PG8_SA(b, h) + aoff + m * 2048 + k * 1024); } while (0)
; #define PG8_LDB(dst, b, h) do { _Pragma("unroll") for (int n = 0; n < 2; ++n) _Pragma("unroll") for (int k = 0; k < 2; ++k) dst[n][k] = *(const LAS bf16x8*)(lds + PG8_SB(b, h) + boff + n * 2048 + k * 1024); } while (0)
; #define PG8_MMA(ai, bj, At, Bt) do { __builtin_amdgcn_s_setprio(1); _Pragma("unroll") for (int m = 0; m < 4; ++m) _Pragma("unroll") for (int n = 0; n < 2; ++n) _Pragma("unroll") for (int k = 0; k < 2; ++k) \
;         acc[ai][bj][m][n] = __builtin_amdgcn_mfma_f32_16x16x32_bf16(Bt[n][k], At[m][k], acc[ai][bj][m][n], 0, 0, 0); __builtin_amdgcn_s_setprio(0); } while (0)
; #define PG8_WAIT_V(n) asm volatile("s_waitcnt vmcnt(" #n ")" ::: "memory")
; #define PG8_WAIT_L(n) asm volatile("s_waitcnt lgkmcnt(" #n ")" ::: "memory")
; #define PG8_BAR __builtin_amdgcn_s_barrier()
; #define PG8_SCHED __builtin_amdgcn_sched_barrier(0)
; template <class Epi, class Sched>
; DI void gemm_phase(const int wv, LAS unsigned char* lds, const int lda, const int ldb, const int K, const Sched& S, const Epi& E) {
;     ...
;             PG8_WAIT_V(8); PG8_WAIT_L(0); PG8_BAR; PG8_MMA(1, 0, At, B0); PG8_MMA(1, 1, At, B1); PG8_BAR; PG8_SCHED;
;             PG8_LDB(B0, 1, 0); PG8_LDB(B1, 1, 1); PG8_SCHED; PG8_LDA(At, 1, 0); PG8_STAGE(PG8_SA(0, 1), a2 + hstepA, voffA);
;             PG8_WAIT_V(8); PG8_WAIT_L(0); PG8_BAR; PG8_MMA(0, 0, At, B0); PG8_MMA(0, 1, At, B1); PG8_BAR; PG8_SCHED;
	s_setprio 1
	v_mfma_f32_16x16x32_bf16 v[60:63], v[128:131], v[180:183], v[60:63]
	v_mfma_f32_16x16x32_bf16 v[56:59], v[136:139], v[180:183], v[56:59]
	v_mfma_f32_16x16x32_bf16 v[52:55], v[128:131], v[188:191], v[52:55]
	v_mfma_f32_16x16x32_bf16 v[44:47], v[136:139], v[188:191], v[44:47]
	v_mfma_f32_16x16x32_bf16 v[36:39], v[128:131], v[196:199], v[36:39]
	v_mfma_f32_16x16x32_bf16 v[28:31], v[136:139], v[196:199], v[28:31]
	v_mfma_f32_16x16x32_bf16 v[20:23], v[128:131], v[214:217], v[20:23]
	v_mfma_f32_16x16x32_bf16 v[12:15], v[136:139], v[214:217], v[12:15]
	v_mfma_f32_16x16x32_bf16 v[60:63], v[132:135], v[184:187], v[60:63]
	v_mfma_f32_16x16x32_bf16 v[56:59], v[140:143], v[184:187], v[56:59]
	v_mfma_f32_16x16x32_bf16 v[52:55], v[132:135], v[192:195], v[52:55]
	v_mfma_f32_16x16x32_bf16 v[44:47], v[140:143], v[192:195], v[44:47]
	v_mfma_f32_16x16x32_bf16 v[36:39], v[132:135], v[210:213], v[36:39]
	v_mfma_f32_16x16x32_bf16 v[28:31], v[140:143], v[210:213], v[28:31]
	v_mfma_f32_16x16x32_bf16 v[20:23], v[132:135], v[218:221], v[20:23]
	v_mfma_f32_16x16x32_bf16 v[12:15], v[140:143], v[218:221], v[12:15]
	v_mfma_f32_16x16x32_bf16 v[48:51], v[162:165], v[180:183], v[48:51]
	v_mfma_f32_16x16x32_bf16 v[40:43], v[172:175], v[180:183], v[40:43]
	v_mfma_f32_16x16x32_bf16 v[32:35], v[162:165], v[188:191], v[32:35]
	v_mfma_f32_16x16x32_bf16 v[24:27], v[172:175], v[188:191], v[24:27]
	v_mfma_f32_16x16x32_bf16 v[16:19], v[162:165], v[196:199], v[16:19]
	v_mfma_f32_16x16x32_bf16 v[8:11], v[172:175], v[196:199], v[8:11]
	v_mfma_f32_16x16x32_bf16 v[4:7], v[162:165], v[214:217], v[4:7]
	v_mfma_f32_16x16x32_bf16 v[0:3], v[172:175], v[214:217], v[0:3]
	v_mfma_f32_16x16x32_bf16 v[48:51], v[168:171], v[184:187], v[48:51]
	v_mfma_f32_16x16x32_bf16 v[40:43], v[176:179], v[184:187], v[40:43]
	v_mfma_f32_16x16x32_bf16 v[32:35], v[168:171], v[192:195], v[32:35]
	v_mfma_f32_16x16x32_bf16 v[24:27], v[176:179], v[192:195], v[24:27]
	v_mfma_f32_16x16x32_bf16 v[16:19], v[168:171], v[210:213], v[16:19]
	v_mfma_f32_16x16x32_bf16 v[8:11], v[176:179], v[210:213], v[8:11]
	v_mfma_f32_16x16x32_bf16 v[4:7], v[168:171], v[218:221], v[4:7]
	v_mfma_f32_16x16x32_bf16 v[0:3], v[176:179], v[218:221], v[0:3]
	s_setprio 0
	s_barrier
	s_add_i32 s42, 0, 0x18000
	s_add_i32 s43, 0, 0x1c000
	v_add_u32_e32 v140, s42, v157
	v_add_u32_e32 v176, s43, v157
	ds_read_b128 v[128:131], v140
	ds_read_b128 v[132:135], v140 offset:1024
	ds_read_b128 v[136:139], v140 offset:2048
	ds_read_b128 v[140:143], v140 offset:3072
	ds_read_b128 v[162:165], v176
	ds_read_b128 v[168:171], v176 offset:1024
	ds_read_b128 v[172:175], v176 offset:2048
	ds_read_b128 v[176:179], v176 offset:3072
	s_add_u32 s20, s20, 0x80000
	s_addc_u32 s21, s21, 0
	s_mov_b32 m0, s29
	v_lshl_add_u64 v[228:229], s[20:21], 0, v[148:149]
	ds_read_b128 v[180:183], v159 offset:32768
	ds_read_b128 v[184:187], v159 offset:33792
	ds_read_b128 v[188:191], v159 offset:34816
	ds_read_b128 v[192:195], v159 offset:35840
	ds_read_b128 v[196:199], v159 offset:36864
	ds_read_b128 v[210:213], v159 offset:37888
	ds_read_b128 v[214:217], v159 offset:38912
	ds_read_b128 v[218:221], v159 offset:39936
	global_load_lds_dwordx4 v[228:229], off
	v_lshl_add_u64 v[228:229], s[20:21], 0, v[146:147]
	s_mov_b32 m0, s30
	s_nop 0
	global_load_lds_dwordx4 v[228:229], off
	s_waitcnt vmcnt(8) lgkmcnt(0)
	s_barrier
	s_setprio 1
	v_mfma_f32_16x16x32_bf16 v[124:127], v[128:131], v[180:183], v[124:127]
	v_mfma_f32_16x16x32_bf16 v[120:123], v[136:139], v[180:183], v[120:123]
	v_mfma_f32_16x16x32_bf16 v[116:119], v[128:131], v[188:191], v[116:119]
	v_mfma_f32_16x16x32_bf16 v[108:111], v[136:139], v[188:191], v[108:111]
	v_mfma_f32_16x16x32_bf16 v[100:103], v[128:131], v[196:199], v[100:103]
	v_mfma_f32_16x16x32_bf16 v[92:95], v[136:139], v[196:199], v[92:95]
	v_mfma_f32_16x16x32_bf16 v[84:87], v[128:131], v[214:217], v[84:87]
	v_mfma_f32_16x16x32_bf16 v[76:79], v[136:139], v[214:217], v[76:79]
	v_mfma_f32_16x16x32_bf16 v[124:127], v[132:135], v[184:187], v[124:127]
	v_mfma_f32_16x16x32_bf16 v[120:123], v[140:143], v[184:187], v[120:123]
	v_mfma_f32_16x16x32_bf16 v[116:119], v[132:135], v[192:195], v[116:119]
	v_mfma_f32_16x16x32_bf16 v[108:111], v[140:143], v[192:195], v[108:111]
	v_mfma_f32_16x16x32_bf16 v[100:103], v[132:135], v[210:213], v[100:103]
	v_mfma_f32_16x16x32_bf16 v[92:95], v[140:143], v[210:213], v[92:95]
	v_mfma_f32_16x16x32_bf16 v[84:87], v[132:135], v[218:221], v[84:87]
	v_mfma_f32_16x16x32_bf16 v[76:79], v[140:143], v[218:221], v[76:79]
	v_mfma_f32_16x16x32_bf16 v[112:115], v[162:165], v[180:183], v[112:115]
	v_mfma_f32_16x16x32_bf16 v[104:107], v[172:175], v[180:183], v[104:107]
	v_mfma_f32_16x16x32_bf16 v[96:99], v[162:165], v[188:191], v[96:99]
	v_mfma_f32_16x16x32_bf16 v[88:91], v[172:175], v[188:191], v[88:91]
	v_mfma_f32_16x16x32_bf16 v[80:83], v[162:165], v[196:199], v[80:83]
	v_mfma_f32_16x16x32_bf16 v[72:75], v[172:175], v[196:199], v[72:75]
	v_mfma_f32_16x16x32_bf16 v[68:71], v[162:165], v[214:217], v[68:71]
	v_mfma_f32_16x16x32_bf16 v[64:67], v[172:175], v[214:217], v[64:67]
	v_mfma_f32_16x16x32_bf16 v[112:115], v[168:171], v[184:187], v[112:115]
	v_mfma_f32_16x16x32_bf16 v[104:107], v[176:179], v[184:187], v[104:107]
	v_mfma_f32_16x16x32_bf16 v[96:99], v[168:171], v[192:195], v[96:99]
	v_mfma_f32_16x16x32_bf16 v[88:91], v[176:179], v[192:195], v[88:91]
	v_mfma_f32_16x16x32_bf16 v[80:83], v[168:171], v[210:213], v[80:83]
	v_mfma_f32_16x16x32_bf16 v[72:75], v[176:179], v[210:213], v[72:75]
	v_mfma_f32_16x16x32_bf16 v[68:71], v[168:171], v[218:221], v[68:71]
	v_mfma_f32_16x16x32_bf16 v[64:67], v[176:179], v[218:221], v[64:67]
	s_setprio 0
	s_barrier
; #define PG8_STAGE(bufoff, gbase, voff) do { _Pragma("unroll") for (int _i = 0; _i < 2; ++_i) \
;         __builtin_amdgcn_global_load_lds((const unsigned*)((const char*)(gbase) + (voff)[_i]), (LAS unsigned*)(lds + (bufoff) + ldsw + _i * 8192), 16, 0, 0); } while (0)
; #define PG8_LDA(dst, b, h) do { _Pragma("unroll") for (int m = 0; m < 4; ++m) _Pragma("unroll") for (int k = 0; k < 2; ++k) dst[m][k] = *(const LAS bf16x8*)(lds + PG8_SA(b, h) + aoff + m * 2048 + k * 1024); } while (0)
; #define PG8_MMA(ai, bj, At, Bt) do { __builtin_amdgcn_s_setprio(1); _Pragma("unroll") for (int m = 0; m < 4; ++m) _Pragma("unroll") for (int n = 0; n < 2; ++n) _Pragma("unroll") for (int k = 0; k < 2; ++k) \
;         acc[ai][bj][m][n] = __builtin_amdgcn_mfma_f32_16x16x32_bf16(Bt[n][k], At[m][k], acc[ai][bj][m][n], 0, 0, 0); __builtin_amdgcn_s_setprio(0); } while (0)
; #define PG8_WAIT_V(n) asm volatile("s_waitcnt vmcnt(" #n ")" ::: "memory")
; #define PG8_WAIT_L(n) asm volatile("s_waitcnt lgkmcnt(" #n ")" ::: "memory")
; #define PG8_BAR __builtin_amdgcn_s_barrier()
; #define PG8_SCHED __builtin_amdgcn_sched_barrier(0)
; template <class Epi, class Sched>
; DI void gemm_phase(const int wv, LAS unsigned char* lds, const int lda, const int ldb, const int K, const Sched& S, const Epi& E) {
;     ...
;             PG8_LDA(At, 1, 1); PG8_STAGE(PG8_SB(1, 0), b3, voffB); PG8_STAGE(PG8_SB(1, 1), b3 + hstepB, voffB); PG8_STAGE(PG8_SA(1, 0), a3, voffA);
;             PG8_WAIT_V(8); PG8_WAIT_L(0); PG8_BAR; PG8_MMA(1, 0, At, B0); PG8_MMA(1, 1, At, B1); PG8_BAR; PG8_SCHED;
;         }
;         if (wr == 0) PG8_BAR;
	s_add_i32 s20, s42, s26
	v_lshl_add_u64 v[154:155], v[154:155], 0, s[78:79]
	s_mov_b32 m0, s20
	ds_read_b128 v[180:183], v159 offset:49152
	ds_read_b128 v[184:187], v159 offset:50176
	ds_read_b128 v[188:191], v159 offset:51200
	ds_read_b128 v[192:195], v159 offset:52224
	ds_read_b128 v[196:199], v159 offset:53248
	ds_read_b128 v[210:213], v159 offset:54272
	ds_read_b128 v[214:217], v159 offset:55296
	ds_read_b128 v[218:221], v159 offset:56320
	global_load_lds_dwordx4 v[154:155], off
	s_add_i32 m0, s20, 0x2000
	s_add_u32 s18, s18, 0x80080
	v_lshl_add_u64 v[154:155], v[222:223], 0, s[78:79]
	s_addc_u32 s19, s19, 0
	s_add_i32 s20, s43, s26
	global_load_lds_dwordx4 v[154:155], off
	v_lshl_add_u64 v[154:155], s[18:19], 0, v[160:161]
	s_mov_b32 m0, s20
	s_nop 0
	global_load_lds_dwordx4 v[154:155], off
	v_lshl_add_u64 v[154:155], s[18:19], 0, v[144:145]
	s_add_i32 m0, s20, 0x2000
	s_nop 0
	global_load_lds_dwordx4 v[154:155], off
	v_lshl_add_u64 v[154:155], v[224:225], 0, s[78:79]
	s_mov_b32 m0, s35
	s_nop 0
	global_load_lds_dwordx4 v[154:155], off
	v_lshl_add_u64 v[154:155], v[226:227], 0, s[78:79]
	s_mov_b32 m0, s36
	s_nop 0
	global_load_lds_dwordx4 v[154:155], off
	s_waitcnt vmcnt(8) lgkmcnt(0)
	s_barrier
	s_setprio 1
	v_mfma_f32_16x16x32_bf16 v[60:63], v[128:131], v[180:183], v[60:63]
	v_mfma_f32_16x16x32_bf16 v[56:59], v[136:139], v[180:183], v[56:59]
	v_mfma_f32_16x16x32_bf16 v[52:55], v[128:131], v[188:191], v[52:55]
	v_mfma_f32_16x16x32_bf16 v[44:47], v[136:139], v[188:191], v[44:47]
	v_mfma_f32_16x16x32_bf16 v[36:39], v[128:131], v[196:199], v[36:39]
	v_mfma_f32_16x16x32_bf16 v[28:31], v[136:139], v[196:199], v[28:31]
	v_mfma_f32_16x16x32_bf16 v[20:23], v[128:131], v[214:217], v[20:23]
	v_mfma_f32_16x16x32_bf16 v[12:15], v[136:139], v[214:217], v[12:15]
	v_mfma_f32_16x16x32_bf16 v[60:63], v[132:135], v[184:187], v[60:63]
	v_mfma_f32_16x16x32_bf16 v[56:59], v[140:143], v[184:187], v[56:59]
	v_mfma_f32_16x16x32_bf16 v[52:55], v[132:135], v[192:195], v[52:55]
	v_mfma_f32_16x16x32_bf16 v[44:47], v[140:143], v[192:195], v[44:47]
	v_mfma_f32_16x16x32_bf16 v[36:39], v[132:135], v[210:213], v[36:39]
	v_mfma_f32_16x16x32_bf16 v[28:31], v[140:143], v[210:213], v[28:31]
	v_mfma_f32_16x16x32_bf16 v[20:23], v[132:135], v[218:221], v[20:23]
	v_mfma_f32_16x16x32_bf16 v[12:15], v[140:143], v[218:221], v[12:15]
	v_mfma_f32_16x16x32_bf16 v[48:51], v[162:165], v[180:183], v[48:51]
	v_mfma_f32_16x16x32_bf16 v[40:43], v[172:175], v[180:183], v[40:43]
	v_mfma_f32_16x16x32_bf16 v[32:35], v[162:165], v[188:191], v[32:35]
	v_mfma_f32_16x16x32_bf16 v[24:27], v[172:175], v[188:191], v[24:27]
	v_mfma_f32_16x16x32_bf16 v[16:19], v[162:165], v[196:199], v[16:19]
	v_mfma_f32_16x16x32_bf16 v[8:11], v[172:175], v[196:199], v[8:11]
	v_mfma_f32_16x16x32_bf16 v[4:7], v[162:165], v[214:217], v[4:7]
	v_mfma_f32_16x16x32_bf16 v[0:3], v[172:175], v[214:217], v[0:3]
	v_mfma_f32_16x16x32_bf16 v[48:51], v[168:171], v[184:187], v[48:51]
	v_mfma_f32_16x16x32_bf16 v[40:43], v[176:179], v[184:187], v[40:43]
	v_mfma_f32_16x16x32_bf16 v[32:35], v[168:171], v[192:195], v[32:35]
	v_mfma_f32_16x16x32_bf16 v[24:27], v[176:179], v[192:195], v[24:27]
	v_mfma_f32_16x16x32_bf16 v[16:19], v[168:171], v[210:213], v[16:19]
	v_mfma_f32_16x16x32_bf16 v[8:11], v[176:179], v[210:213], v[8:11]
	v_mfma_f32_16x16x32_bf16 v[4:7], v[168:171], v[218:221], v[4:7]
	v_mfma_f32_16x16x32_bf16 v[0:3], v[176:179], v[218:221], v[0:3]
	s_setprio 0
	s_barrier
	s_add_i32 s41, s41, 2
	s_add_u32 s11, s11, 0x100
	s_addc_u32 s40, s40, 0
	s_add_u32 s16, s16, 0x100
	s_addc_u32 s17, s17, 0
	s_cmp_gt_u32 s41, 29
	s_cbranch_scc0 .LBB0_686
	s_and_b64 vcc, exec, s[8:9]
	s_cbranch_vccz .LBB0_689
	s_barrier

; #define PG8_STAGE(bufoff, gbase, voff) do { _Pragma("unroll") for (int _i = 0; _i < 2; ++_i) \
;         __builtin_amdgcn_global_load_lds((const unsigned*)((const char*)(gbase) + (voff)[_i]), (LAS unsigned*)(lds + (bufoff) + ldsw + _i * 8192), 16, 0, 0); } while (0)
; #define PG8_LDA(dst, b, h) do { _Pragma("unroll") for (int m = 0; m < 4; ++m) _Pragma("unroll") for (int k = 0; k < 2; ++k) dst[m][k] = *(const LAS bf16x8*)(lds + PG8_SA(b, h) + aoff + m * 2048 + k * 1024); } while (0)
; #define PG8_LDB(dst, b, h) do { _Pragma("unroll") for (int n = 0; n < 2; ++n) _Pragma("unroll") for (int k = 0; k < 2; ++k) dst[n][k] = *(const LAS bf16x8*)(lds + PG8_SB(b, h) + boff + n * 2048 + k * 1024); } while (0)
; #define PG8_MMA(ai, bj, At, Bt) do { __builtin_amdgcn_s_setprio(1); _Pragma("unroll") for (int m = 0; m < 4; ++m) _Pragma("unroll") for (int n = 0; n < 2; ++n) _Pragma("unroll") for (int k = 0; k < 2; ++k) \
;         acc[ai][bj][m][n] = __builtin_amdgcn_mfma_f32_16x16x32_bf16(Bt[n][k], At[m][k], acc[ai][bj][m][n], 0, 0, 0); __builtin_amdgcn_s_setprio(0); } while (0)
; #define PG8_WAIT_V(n) asm volatile("s_waitcnt vmcnt(" #n ")" ::: "memory")
; #define PG8_WAIT_L(n) asm volatile("s_waitcnt lgkmcnt(" #n ")" ::: "memory")
; #define PG8_BAR __builtin_amdgcn_s_barrier()
; #define PG8_SCHED __builtin_amdgcn_sched_barrier(0)
; template <class Epi, class Sched>
; DI void gemm_phase(const int wv, LAS unsigned char* lds, const int lda, const int ldb, const int K, const Sched& S, const Epi& E) {
;     ...
;             const bool last = (t == nt - 2);
;             const char* a1 = cA + (size_t)(t + 1) * kstep;
;             const char* a2 = last ? nA : cA + (size_t)(t + 2) * kstep; const char* b2 = last ? nB : cB + (size_t)(t + 2) * kstep;
;             const char* a3 = a2 + kstep; const char* b3 = b2 + kstep;
;             PG8_LDB(B0, 0, 0); PG8_LDB(B1, 0, 1); PG8_SCHED; PG8_LDA(At, 0, 0); PG8_STAGE(PG8_SA(1, 1), a1 + hstepA, voffA);
;             PG8_WAIT_V(8); PG8_WAIT_L(0); PG8_BAR; PG8_MMA(0, 0, At, B0); PG8_MMA(0, 1, At, B1); PG8_BAR; PG8_SCHED;
;             PG8_LDA(At, 0, 1); PG8_STAGE(PG8_SB(0, 0), b2, voffB); PG8_STAGE(PG8_SB(0, 1), b2 + hstepB, voffB); PG8_STAGE(PG8_SA(0, 0), a2, voffA);
;             PG8_WAIT_V(8); PG8_WAIT_L(0); PG8_BAR; PG8_MMA(1, 0, At, B0); PG8_MMA(1, 1, At, B1); PG8_BAR; PG8_SCHED;
.LBB0_825:
	s_add_u32 s20, s18, 0xfff80080
	s_addc_u32 s21, s19, -1
	s_add_i32 s42, 0, 0x10000
	s_cmp_eq_u32 s41, 28
	s_cselect_b32 s23, s15, s21
	s_cselect_b32 s22, s14, s20
	s_cselect_b32 s21, s17, s40
	s_cselect_b32 s20, s16, s13
	s_add_i32 s44, 0, 0x14000
	v_add_u32_e32 v154, s42, v139
	v_add_u32_e32 v158, s44, v139
	ds_read_b128 v[142:145], v154
	ds_read_b128 v[146:149], v154 offset:1024
	ds_read_b128 v[150:153], v154 offset:2048
	ds_read_b128 v[154:157], v154 offset:3072
	ds_read_b128 v[162:165], v158
	ds_read_b128 v[168:171], v158 offset:1024
	ds_read_b128 v[172:175], v158 offset:2048
	ds_read_b128 v[176:179], v158 offset:3072
	v_lshl_add_u64 v[158:159], s[18:19], 0, v[136:137]
	s_add_i32 m0, s29, 0xc000
	ds_read_b128 v[180:183], v141
	ds_read_b128 v[184:187], v141 offset:1024
	ds_read_b128 v[188:191], v141 offset:2048
	ds_read_b128 v[192:195], v141 offset:3072
	ds_read_b128 v[196:199], v141 offset:4096
	ds_read_b128 v[210:213], v141 offset:5120
	ds_read_b128 v[214:217], v141 offset:6144
	ds_read_b128 v[218:221], v141 offset:7168
	global_load_lds_dwordx4 v[158:159], off
	v_lshl_add_u64 v[158:159], s[18:19], 0, v[134:135]
	s_add_i32 m0, s29, 0xe000
	s_nop 0
	global_load_lds_dwordx4 v[158:159], off
	s_waitcnt vmcnt(8) lgkmcnt(0)
	s_barrier
	s_setprio 1
	v_mfma_f32_16x16x32_bf16 v[124:127], v[142:145], v[180:183], v[124:127]
	v_mfma_f32_16x16x32_bf16 v[120:123], v[150:153], v[180:183], v[120:123]
	v_mfma_f32_16x16x32_bf16 v[108:111], v[142:145], v[188:191], v[108:111]
	v_mfma_f32_16x16x32_bf16 v[104:107], v[150:153], v[188:191], v[104:107]
	v_mfma_f32_16x16x32_bf16 v[92:95], v[142:145], v[196:199], v[92:95]
	v_mfma_f32_16x16x32_bf16 v[88:91], v[150:153], v[196:199], v[88:91]
	v_mfma_f32_16x16x32_bf16 v[76:79], v[142:145], v[214:217], v[76:79]
	v_mfma_f32_16x16x32_bf16 v[72:75], v[150:153], v[214:217], v[72:75]
	v_mfma_f32_16x16x32_bf16 v[124:127], v[146:149], v[184:187], v[124:127]
	v_mfma_f32_16x16x32_bf16 v[120:123], v[154:157], v[184:187], v[120:123]
	v_mfma_f32_16x16x32_bf16 v[108:111], v[146:149], v[192:195], v[108:111]
	v_mfma_f32_16x16x32_bf16 v[104:107], v[154:157], v[192:195], v[104:107]
	v_mfma_f32_16x16x32_bf16 v[92:95], v[146:149], v[210:213], v[92:95]
	v_mfma_f32_16x16x32_bf16 v[88:91], v[154:157], v[210:213], v[88:91]
	v_mfma_f32_16x16x32_bf16 v[76:79], v[146:149], v[218:221], v[76:79]
	v_mfma_f32_16x16x32_bf16 v[72:75], v[154:157], v[218:221], v[72:75]
	v_mfma_f32_16x16x32_bf16 v[116:119], v[162:165], v[180:183], v[116:119]
	v_mfma_f32_16x16x32_bf16 v[112:115], v[172:175], v[180:183], v[112:115]
	v_mfma_f32_16x16x32_bf16 v[100:103], v[162:165], v[188:191], v[100:103]
	v_mfma_f32_16x16x32_bf16 v[96:99], v[172:175], v[188:191], v[96:99]
	v_mfma_f32_16x16x32_bf16 v[84:87], v[162:165], v[196:199], v[84:87]
	v_mfma_f32_16x16x32_bf16 v[80:83], v[172:175], v[196:199], v[80:83]
	v_mfma_f32_16x16x32_bf16 v[68:71], v[162:165], v[214:217], v[68:71]
	v_mfma_f32_16x16x32_bf16 v[64:67], v[172:175], v[214:217], v[64:67]
	v_mfma_f32_16x16x32_bf16 v[116:119], v[168:171], v[184:187], v[116:119]
	v_mfma_f32_16x16x32_bf16 v[112:115], v[176:179], v[184:187], v[112:115]
	v_mfma_f32_16x16x32_bf16 v[100:103], v[168:171], v[192:195], v[100:103]
	v_mfma_f32_16x16x32_bf16 v[96:99], v[176:179], v[192:195], v[96:99]
	v_mfma_f32_16x16x32_bf16 v[84:87], v[168:171], v[210:213], v[84:87]
	v_mfma_f32_16x16x32_bf16 v[80:83], v[176:179], v[210:213], v[80:83]
	v_mfma_f32_16x16x32_bf16 v[68:71], v[168:171], v[218:221], v[68:71]
	v_mfma_f32_16x16x32_bf16 v[64:67], v[176:179], v[218:221], v[64:67]
	s_setprio 0
	s_barrier
	s_add_i32 s42, s42, s28
	v_lshl_add_u64 v[158:159], s[20:21], 0, v[160:161]
	s_mov_b32 m0, s42
	ds_read_b128 v[180:183], v141 offset:16384
	ds_read_b128 v[184:187], v141 offset:17408
	ds_read_b128 v[188:191], v141 offset:18432
	ds_read_b128 v[192:195], v141 offset:19456
	ds_read_b128 v[196:199], v141 offset:20480
	ds_read_b128 v[210:213], v141 offset:21504
	ds_read_b128 v[214:217], v141 offset:22528
	ds_read_b128 v[218:221], v141 offset:23552
	global_load_lds_dwordx4 v[158:159], off
	s_add_i32 m0, s42, 0x2000
	s_add_u32 s42, s20, 0x80000
	v_lshl_add_u64 v[222:223], s[20:21], 0, v[128:129]
	s_addc_u32 s43, s21, 0
	s_add_i32 s44, s44, s28
	global_load_lds_dwordx4 v[222:223], off
	v_lshl_add_u64 v[224:225], s[42:43], 0, v[160:161]
	s_mov_b32 m0, s44
	v_lshl_add_u64 v[226:227], s[22:23], 0, v[130:131]
	global_load_lds_dwordx4 v[224:225], off
	v_lshl_add_u64 v[224:225], s[42:43], 0, v[128:129]
	s_add_i32 m0, s44, 0x2000
	s_nop 0
	global_load_lds_dwordx4 v[224:225], off
	v_lshl_add_u64 v[224:225], s[22:23], 0, v[132:133]
	s_mov_b32 m0, s29
	s_nop 0
	global_load_lds_dwordx4 v[224:225], off
	s_mov_b32 m0, s30
	s_nop 0
	global_load_lds_dwordx4 v[226:227], off
	s_waitcnt vmcnt(8) lgkmcnt(0)
	s_barrier
; #define PG8_STAGE(bufoff, gbase, voff) do { _Pragma("unroll") for (int _i = 0; _i < 2; ++_i) \
;         __builtin_amdgcn_global_load_lds((const unsigned*)((const char*)(gbase) + (voff)[_i]), (LAS unsigned*)(lds + (bufoff) + ldsw + _i * 8192), 16, 0, 0); } while (0)
; #define PG8_LDA(dst, b, h) do { _Pragma("unroll") for (int m = 0; m < 4; ++m) _Pragma("unroll") for (int k = 0; k < 2; ++k) dst[m][k] = *(const LAS bf16x8*)(lds + PG8_SA(b, h) + aoff + m * 2048 + k * 1024); } while (0)
; #define PG8_LDB(dst, b, h) do { _Pragma("unroll") for (int n = 0; n < 2; ++n) _Pragma("unroll") for (int k = 0; k < 2; ++k) dst[n][k] = *(const LAS bf16x8*)(lds + PG8_SB(b, h) + boff + n * 2048 + k * 1024); } while (0)
; #define PG8_MMA(ai, bj, At, Bt) do { __builtin_amdgcn_s_setprio(1); _Pragma("unroll") for (int m = 0; m < 4; ++m) _Pragma("unroll") for (int n = 0; n < 2; ++n) _Pragma("unroll") for (int k = 0; k < 2; ++k) \
;         acc[ai][bj][m][n] = __builtin_amdgcn_mfma_f32_16x16x32_bf16(Bt[n][k], At[m][k], acc[ai][bj][m][n], 0, 0, 0); __builtin_amdgcn_s_setprio(0); } while (0)
; #define PG8_WAIT_V(n) asm volatile("s_waitcnt vmcnt(" #n ")" ::: "memory")
; #define PG8_WAIT_L(n) asm volatile("s_waitcnt lgkmcnt(" #n ")" ::: "memory")
; #define PG8_BAR __builtin_amdgcn_s_barrier()
; #define PG8_SCHED __builtin_amdgcn_sched_barrier(0)
; template <class Epi, class Sched>
; DI void gemm_phase(const int wv, LAS unsigned char* lds, const int lda, const int ldb, const int K, const Sched& S, const Epi& E) {
;     ...
;             PG8_WAIT_V(8); PG8_WAIT_L(0); PG8_BAR; PG8_MMA(1, 0, At, B0); PG8_MMA(1, 1, At, B1); PG8_BAR; PG8_SCHED;
;             PG8_LDB(B0, 1, 0); PG8_LDB(B1, 1, 1); PG8_SCHED; PG8_LDA(At, 1, 0); PG8_STAGE(PG8_SA(0, 1), a2 + hstepA, voffA);
;             PG8_WAIT_V(8); PG8_WAIT_L(0); PG8_BAR; PG8_MMA(0, 0, At, B0); PG8_MMA(0, 1, At, B1); PG8_BAR; PG8_SCHED;
	s_setprio 1
	v_mfma_f32_16x16x32_bf16 v[60:63], v[142:145], v[180:183], v[60:63]
	v_mfma_f32_16x16x32_bf16 v[56:59], v[150:153], v[180:183], v[56:59]
	v_mfma_f32_16x16x32_bf16 v[44:47], v[142:145], v[188:191], v[44:47]
	v_mfma_f32_16x16x32_bf16 v[40:43], v[150:153], v[188:191], v[40:43]
	v_mfma_f32_16x16x32_bf16 v[28:31], v[142:145], v[196:199], v[28:31]
	v_mfma_f32_16x16x32_bf16 v[24:27], v[150:153], v[196:199], v[24:27]
	v_mfma_f32_16x16x32_bf16 v[12:15], v[142:145], v[214:217], v[12:15]
	v_mfma_f32_16x16x32_bf16 v[8:11], v[150:153], v[214:217], v[8:11]
	v_mfma_f32_16x16x32_bf16 v[60:63], v[146:149], v[184:187], v[60:63]
	v_mfma_f32_16x16x32_bf16 v[56:59], v[154:157], v[184:187], v[56:59]
	v_mfma_f32_16x16x32_bf16 v[44:47], v[146:149], v[192:195], v[44:47]
	v_mfma_f32_16x16x32_bf16 v[40:43], v[154:157], v[192:195], v[40:43]
	v_mfma_f32_16x16x32_bf16 v[28:31], v[146:149], v[210:213], v[28:31]
	v_mfma_f32_16x16x32_bf16 v[24:27], v[154:157], v[210:213], v[24:27]
	v_mfma_f32_16x16x32_bf16 v[12:15], v[146:149], v[218:221], v[12:15]
	v_mfma_f32_16x16x32_bf16 v[8:11], v[154:157], v[218:221], v[8:11]
	v_mfma_f32_16x16x32_bf16 v[52:55], v[162:165], v[180:183], v[52:55]
	v_mfma_f32_16x16x32_bf16 v[48:51], v[172:175], v[180:183], v[48:51]
	v_mfma_f32_16x16x32_bf16 v[36:39], v[162:165], v[188:191], v[36:39]
	v_mfma_f32_16x16x32_bf16 v[32:35], v[172:175], v[188:191], v[32:35]
	v_mfma_f32_16x16x32_bf16 v[20:23], v[162:165], v[196:199], v[20:23]
	v_mfma_f32_16x16x32_bf16 v[16:19], v[172:175], v[196:199], v[16:19]
	v_mfma_f32_16x16x32_bf16 v[4:7], v[162:165], v[214:217], v[4:7]
	v_mfma_f32_16x16x32_bf16 v[0:3], v[172:175], v[214:217], v[0:3]
	v_mfma_f32_16x16x32_bf16 v[52:55], v[168:171], v[184:187], v[52:55]
	v_mfma_f32_16x16x32_bf16 v[48:51], v[176:179], v[184:187], v[48:51]
	v_mfma_f32_16x16x32_bf16 v[36:39], v[168:171], v[192:195], v[36:39]
	v_mfma_f32_16x16x32_bf16 v[32:35], v[176:179], v[192:195], v[32:35]
	v_mfma_f32_16x16x32_bf16 v[20:23], v[168:171], v[210:213], v[20:23]
	v_mfma_f32_16x16x32_bf16 v[16:19], v[176:179], v[210:213], v[16:19]
	v_mfma_f32_16x16x32_bf16 v[4:7], v[168:171], v[218:221], v[4:7]
	v_mfma_f32_16x16x32_bf16 v[0:3], v[176:179], v[218:221], v[0:3]
	s_setprio 0
	s_barrier
	s_add_i32 s42, 0, 0x18000
	s_add_i32 s43, 0, 0x1c000
	v_add_u32_e32 v154, s42, v139
	v_add_u32_e32 v176, s43, v139
	ds_read_b128 v[142:145], v154
	ds_read_b128 v[146:149], v154 offset:1024
	ds_read_b128 v[150:153], v154 offset:2048
	ds_read_b128 v[154:157], v154 offset:3072
	ds_read_b128 v[162:165], v176
	ds_read_b128 v[168:171], v176 offset:1024
	ds_read_b128 v[172:175], v176 offset:2048
	ds_read_b128 v[176:179], v176 offset:3072
	s_add_u32 s22, s22, 0x80000
	s_addc_u32 s23, s23, 0
	s_mov_b32 m0, s31
	v_lshl_add_u64 v[228:229], s[22:23], 0, v[132:133]
	ds_read_b128 v[180:183], v141 offset:32768
	ds_read_b128 v[184:187], v141 offset:33792
	ds_read_b128 v[188:191], v141 offset:34816
	ds_read_b128 v[192:195], v141 offset:35840
	ds_read_b128 v[196:199], v141 offset:36864
	ds_read_b128 v[210:213], v141 offset:37888
	ds_read_b128 v[214:217], v141 offset:38912
	ds_read_b128 v[218:221], v141 offset:39936
	global_load_lds_dwordx4 v[228:229], off
	v_lshl_add_u64 v[228:229], s[22:23], 0, v[130:131]
	s_mov_b32 m0, s34
	s_nop 0
	global_load_lds_dwordx4 v[228:229], off
	s_waitcnt vmcnt(8) lgkmcnt(0)
	s_barrier
	s_setprio 1
	v_mfma_f32_16x16x32_bf16 v[124:127], v[142:145], v[180:183], v[124:127]
	v_mfma_f32_16x16x32_bf16 v[120:123], v[150:153], v[180:183], v[120:123]
	v_mfma_f32_16x16x32_bf16 v[108:111], v[142:145], v[188:191], v[108:111]
	v_mfma_f32_16x16x32_bf16 v[104:107], v[150:153], v[188:191], v[104:107]
	v_mfma_f32_16x16x32_bf16 v[92:95], v[142:145], v[196:199], v[92:95]
	v_mfma_f32_16x16x32_bf16 v[88:91], v[150:153], v[196:199], v[88:91]
	v_mfma_f32_16x16x32_bf16 v[76:79], v[142:145], v[214:217], v[76:79]
	v_mfma_f32_16x16x32_bf16 v[72:75], v[150:153], v[214:217], v[72:75]
	v_mfma_f32_16x16x32_bf16 v[124:127], v[146:149], v[184:187], v[124:127]
	v_mfma_f32_16x16x32_bf16 v[120:123], v[154:157], v[184:187], v[120:123]
	v_mfma_f32_16x16x32_bf16 v[108:111], v[146:149], v[192:195], v[108:111]
	v_mfma_f32_16x16x32_bf16 v[104:107], v[154:157], v[192:195], v[104:107]
	v_mfma_f32_16x16x32_bf16 v[92:95], v[146:149], v[210:213], v[92:95]
	v_mfma_f32_16x16x32_bf16 v[88:91], v[154:157], v[210:213], v[88:91]
	v_mfma_f32_16x16x32_bf16 v[76:79], v[146:149], v[218:221], v[76:79]
	v_mfma_f32_16x16x32_bf16 v[72:75], v[154:157], v[218:221], v[72:75]
	v_mfma_f32_16x16x32_bf16 v[116:119], v[162:165], v[180:183], v[116:119]
	v_mfma_f32_16x16x32_bf16 v[112:115], v[172:175], v[180:183], v[112:115]
	v_mfma_f32_16x16x32_bf16 v[100:103], v[162:165], v[188:191], v[100:103]
	v_mfma_f32_16x16x32_bf16 v[96:99], v[172:175], v[188:191], v[96:99]
	v_mfma_f32_16x16x32_bf16 v[84:87], v[162:165], v[196:199], v[84:87]
	v_mfma_f32_16x16x32_bf16 v[80:83], v[172:175], v[196:199], v[80:83]
	v_mfma_f32_16x16x32_bf16 v[68:71], v[162:165], v[214:217], v[68:71]
	v_mfma_f32_16x16x32_bf16 v[64:67], v[172:175], v[214:217], v[64:67]
	v_mfma_f32_16x16x32_bf16 v[116:119], v[168:171], v[184:187], v[116:119]
	v_mfma_f32_16x16x32_bf16 v[112:115], v[176:179], v[184:187], v[112:115]
	v_mfma_f32_16x16x32_bf16 v[100:103], v[168:171], v[192:195], v[100:103]
	v_mfma_f32_16x16x32_bf16 v[96:99], v[176:179], v[192:195], v[96:99]
	v_mfma_f32_16x16x32_bf16 v[84:87], v[168:171], v[210:213], v[84:87]
	v_mfma_f32_16x16x32_bf16 v[80:83], v[176:179], v[210:213], v[80:83]
	v_mfma_f32_16x16x32_bf16 v[68:71], v[168:171], v[218:221], v[68:71]
	v_mfma_f32_16x16x32_bf16 v[64:67], v[176:179], v[218:221], v[64:67]
	s_setprio 0
	s_barrier
; #define PG8_STAGE(bufoff, gbase, voff) do { _Pragma("unroll") for (int _i = 0; _i < 2; ++_i) \
;         __builtin_amdgcn_global_load_lds((const unsigned*)((const char*)(gbase) + (voff)[_i]), (LAS unsigned*)(lds + (bufoff) + ldsw + _i * 8192), 16, 0, 0); } while (0)
; #define PG8_LDA(dst, b, h) do { _Pragma("unroll") for (int m = 0; m < 4; ++m) _Pragma("unroll") for (int k = 0; k < 2; ++k) dst[m][k] = *(const LAS bf16x8*)(lds + PG8_SA(b, h) + aoff + m * 2048 + k * 1024); } while (0)
; #define PG8_MMA(ai, bj, At, Bt) do { __builtin_amdgcn_s_setprio(1); _Pragma("unroll") for (int m = 0; m < 4; ++m) _Pragma("unroll") for (int n = 0; n < 2; ++n) _Pragma("unroll") for (int k = 0; k < 2; ++k) \
;         acc[ai][bj][m][n] = __builtin_amdgcn_mfma_f32_16x16x32_bf16(Bt[n][k], At[m][k], acc[ai][bj][m][n], 0, 0, 0); __builtin_amdgcn_s_setprio(0); } while (0)
; #define PG8_WAIT_V(n) asm volatile("s_waitcnt vmcnt(" #n ")" ::: "memory")
; #define PG8_WAIT_L(n) asm volatile("s_waitcnt lgkmcnt(" #n ")" ::: "memory")
; #define PG8_BAR __builtin_amdgcn_s_barrier()
; #define PG8_SCHED __builtin_amdgcn_sched_barrier(0)
; template <class Epi, class Sched>
; DI void gemm_phase(const int wv, LAS unsigned char* lds, const int lda, const int ldb, const int K, const Sched& S, const Epi& E) {
;     ...
;             PG8_LDA(At, 1, 1); PG8_STAGE(PG8_SB(1, 0), b3, voffB); PG8_STAGE(PG8_SB(1, 1), b3 + hstepB, voffB); PG8_STAGE(PG8_SA(1, 0), a3, voffA);
;             PG8_WAIT_V(8); PG8_WAIT_L(0); PG8_BAR; PG8_MMA(1, 0, At, B0); PG8_MMA(1, 1, At, B1); PG8_BAR; PG8_SCHED;
;         }
;         if (wr == 0) PG8_BAR;
	s_add_i32 s22, s42, s28
	v_lshl_add_u64 v[158:159], v[158:159], 0, s[78:79]
	s_mov_b32 m0, s22
	ds_read_b128 v[180:183], v141 offset:49152
	ds_read_b128 v[184:187], v141 offset:50176
	ds_read_b128 v[188:191], v141 offset:51200
	ds_read_b128 v[192:195], v141 offset:52224
	ds_read_b128 v[196:199], v141 offset:53248
	ds_read_b128 v[210:213], v141 offset:54272
	ds_read_b128 v[214:217], v141 offset:55296
	ds_read_b128 v[218:221], v141 offset:56320
	global_load_lds_dwordx4 v[158:159], off
	s_add_i32 m0, s22, 0x2000
	s_add_u32 s20, s20, 0x80080
	v_lshl_add_u64 v[158:159], v[222:223], 0, s[78:79]
	s_addc_u32 s21, s21, 0
	s_add_i32 s22, s43, s28
	global_load_lds_dwordx4 v[158:159], off
	v_lshl_add_u64 v[158:159], s[20:21], 0, v[160:161]
	s_mov_b32 m0, s22
	s_nop 0
	global_load_lds_dwordx4 v[158:159], off
	v_lshl_add_u64 v[158:159], s[20:21], 0, v[128:129]
	s_add_i32 m0, s22, 0x2000
	s_nop 0
	global_load_lds_dwordx4 v[158:159], off
	v_lshl_add_u64 v[158:159], v[224:225], 0, s[78:79]
	s_mov_b32 m0, s35
	s_nop 0
	global_load_lds_dwordx4 v[158:159], off
	v_lshl_add_u64 v[158:159], v[226:227], 0, s[78:79]
	s_mov_b32 m0, s36
	s_nop 0
	global_load_lds_dwordx4 v[158:159], off
	s_waitcnt vmcnt(8) lgkmcnt(0)
	s_barrier
	s_setprio 1
	v_mfma_f32_16x16x32_bf16 v[60:63], v[142:145], v[180:183], v[60:63]
	v_mfma_f32_16x16x32_bf16 v[56:59], v[150:153], v[180:183], v[56:59]
	v_mfma_f32_16x16x32_bf16 v[44:47], v[142:145], v[188:191], v[44:47]
	v_mfma_f32_16x16x32_bf16 v[40:43], v[150:153], v[188:191], v[40:43]
	v_mfma_f32_16x16x32_bf16 v[28:31], v[142:145], v[196:199], v[28:31]
	v_mfma_f32_16x16x32_bf16 v[24:27], v[150:153], v[196:199], v[24:27]
	v_mfma_f32_16x16x32_bf16 v[12:15], v[142:145], v[214:217], v[12:15]
	v_mfma_f32_16x16x32_bf16 v[8:11], v[150:153], v[214:217], v[8:11]
	v_mfma_f32_16x16x32_bf16 v[60:63], v[146:149], v[184:187], v[60:63]
	v_mfma_f32_16x16x32_bf16 v[56:59], v[154:157], v[184:187], v[56:59]
	v_mfma_f32_16x16x32_bf16 v[44:47], v[146:149], v[192:195], v[44:47]
	v_mfma_f32_16x16x32_bf16 v[40:43], v[154:157], v[192:195], v[40:43]
	v_mfma_f32_16x16x32_bf16 v[28:31], v[146:149], v[210:213], v[28:31]
	v_mfma_f32_16x16x32_bf16 v[24:27], v[154:157], v[210:213], v[24:27]
	v_mfma_f32_16x16x32_bf16 v[12:15], v[146:149], v[218:221], v[12:15]
	v_mfma_f32_16x16x32_bf16 v[8:11], v[154:157], v[218:221], v[8:11]
	v_mfma_f32_16x16x32_bf16 v[52:55], v[162:165], v[180:183], v[52:55]
	v_mfma_f32_16x16x32_bf16 v[48:51], v[172:175], v[180:183], v[48:51]
	v_mfma_f32_16x16x32_bf16 v[36:39], v[162:165], v[188:191], v[36:39]
	v_mfma_f32_16x16x32_bf16 v[32:35], v[172:175], v[188:191], v[32:35]
	v_mfma_f32_16x16x32_bf16 v[20:23], v[162:165], v[196:199], v[20:23]
	v_mfma_f32_16x16x32_bf16 v[16:19], v[172:175], v[196:199], v[16:19]
	v_mfma_f32_16x16x32_bf16 v[4:7], v[162:165], v[214:217], v[4:7]
	v_mfma_f32_16x16x32_bf16 v[0:3], v[172:175], v[214:217], v[0:3]
	v_mfma_f32_16x16x32_bf16 v[52:55], v[168:171], v[184:187], v[52:55]
	v_mfma_f32_16x16x32_bf16 v[48:51], v[176:179], v[184:187], v[48:51]
	v_mfma_f32_16x16x32_bf16 v[36:39], v[168:171], v[192:195], v[36:39]
	v_mfma_f32_16x16x32_bf16 v[32:35], v[176:179], v[192:195], v[32:35]
	v_mfma_f32_16x16x32_bf16 v[20:23], v[168:171], v[210:213], v[20:23]
	v_mfma_f32_16x16x32_bf16 v[16:19], v[176:179], v[210:213], v[16:19]
	v_mfma_f32_16x16x32_bf16 v[4:7], v[168:171], v[218:221], v[4:7]
	v_mfma_f32_16x16x32_bf16 v[0:3], v[176:179], v[218:221], v[0:3]
	s_setprio 0
	s_barrier
	s_add_i32 s41, s41, 2
	s_add_u32 s13, s13, 0x100
	s_addc_u32 s40, s40, 0
	s_add_u32 s18, s18, 0x100
	s_addc_u32 s19, s19, 0
	s_cmp_gt_u32 s41, 29
	s_cbranch_scc0 .LBB0_825
	s_and_b64 vcc, exec, s[10:11]
	s_cbranch_vccz .LBB0_828
	s_barrier

; #define PG8_STAGE(bufoff, gbase, voff) do { _Pragma("unroll") for (int _i = 0; _i < 2; ++_i) \
;         __builtin_amdgcn_global_load_lds((const unsigned*)((const char*)(gbase) + (voff)[_i]), (LAS unsigned*)(lds + (bufoff) + ldsw + _i * 8192), 16, 0, 0); } while (0)
; #define PG8_LDA(dst, b, h) do { _Pragma("unroll") for (int m = 0; m < 4; ++m) _Pragma("unroll") for (int k = 0; k < 2; ++k) dst[m][k] = *(const LAS bf16x8*)(lds + PG8_SA(b, h) + aoff + m * 2048 + k * 1024); } while (0)
; #define PG8_LDB(dst, b, h) do { _Pragma("unroll") for (int n = 0; n < 2; ++n) _Pragma("unroll") for (int k = 0; k < 2; ++k) dst[n][k] = *(const LAS bf16x8*)(lds + PG8_SB(b, h) + boff + n * 2048 + k * 1024); } while (0)
; #define PG8_MMA(ai, bj, At, Bt) do { __builtin_amdgcn_s_setprio(1); _Pragma("unroll") for (int m = 0; m < 4; ++m) _Pragma("unroll") for (int n = 0; n < 2; ++n) _Pragma("unroll") for (int k = 0; k < 2; ++k) \
;         acc[ai][bj][m][n] = __builtin_amdgcn_mfma_f32_16x16x32_bf16(Bt[n][k], At[m][k], acc[ai][bj][m][n], 0, 0, 0); __builtin_amdgcn_s_setprio(0); } while (0)
; #define PG8_WAIT_V(n) asm volatile("s_waitcnt vmcnt(" #n ")" ::: "memory")
; #define PG8_WAIT_L(n) asm volatile("s_waitcnt lgkmcnt(" #n ")" ::: "memory")
; #define PG8_BAR __builtin_amdgcn_s_barrier()
; #define PG8_SCHED __builtin_amdgcn_sched_barrier(0)
; template <class Epi, class Sched>
; DI void gemm_phase(const int wv, LAS unsigned char* lds, const int lda, const int ldb, const int K, const Sched& S, const Epi& E) {
;     ...
;             const bool last = (t == nt - 2);
;             const char* a1 = cA + (size_t)(t + 1) * kstep;
;             const char* a2 = last ? nA : cA + (size_t)(t + 2) * kstep; const char* b2 = last ? nB : cB + (size_t)(t + 2) * kstep;
;             const char* a3 = a2 + kstep; const char* b3 = b2 + kstep;
;             PG8_LDB(B0, 0, 0); PG8_LDB(B1, 0, 1); PG8_SCHED; PG8_LDA(At, 0, 0); PG8_STAGE(PG8_SA(1, 1), a1 + hstepA, voffA);
;             PG8_WAIT_V(8); PG8_WAIT_L(0); PG8_BAR; PG8_MMA(0, 0, At, B0); PG8_MMA(0, 1, At, B1); PG8_BAR; PG8_SCHED;
;             PG8_LDA(At, 0, 1); PG8_STAGE(PG8_SB(0, 0), b2, voffB); PG8_STAGE(PG8_SB(0, 1), b2 + hstepB, voffB); PG8_STAGE(PG8_SA(0, 0), a2, voffA);
.LBB0_906:
	s_add_u32 s14, s12, 0xffea0080
	s_addc_u32 s15, s13, -1
	s_add_i32 s40, 0, 0x10000
	s_cmpk_eq_i32 s39, 0x54
	s_cselect_b32 s17, s9, s15
	s_cselect_b32 s16, s8, s14
	s_cselect_b32 s15, s11, s38
	s_cselect_b32 s14, s10, s37
	s_add_i32 s42, 0, 0x14000
	v_add_u32_e32 v76, s40, v157
	v_add_u32_e32 v154, s42, v157
	ds_read_b128 v[48:51], v76
	ds_read_b128 v[52:55], v76 offset:1024
	ds_read_b128 v[72:75], v76 offset:2048
	ds_read_b128 v[76:79], v76 offset:3072
	ds_read_b128 v[162:165], v154
	ds_read_b128 v[168:171], v154 offset:1024
	ds_read_b128 v[172:175], v154 offset:2048
	ds_read_b128 v[176:179], v154 offset:3072
	v_lshl_add_u64 v[154:155], s[12:13], 0, v[152:153]
	s_add_i32 m0, s23, 0xc000
	ds_read_b128 v[180:183], v159
	ds_read_b128 v[184:187], v159 offset:1024
	ds_read_b128 v[188:191], v159 offset:2048
	ds_read_b128 v[192:195], v159 offset:3072
	ds_read_b128 v[196:199], v159 offset:4096
	ds_read_b128 v[210:213], v159 offset:5120
	ds_read_b128 v[214:217], v159 offset:6144
	ds_read_b128 v[218:221], v159 offset:7168
	global_load_lds_dwordx4 v[154:155], off
	v_lshl_add_u64 v[154:155], s[12:13], 0, v[150:151]
	s_add_i32 m0, s23, 0xe000
	s_nop 0
	global_load_lds_dwordx4 v[154:155], off
	s_waitcnt vmcnt(8) lgkmcnt(0)
	s_barrier
	s_setprio 1
	v_mfma_f32_16x16x32_bf16 v[140:143], v[48:51], v[180:183], v[140:143]
	v_mfma_f32_16x16x32_bf16 v[136:139], v[72:75], v[180:183], v[136:139]
	v_mfma_f32_16x16x32_bf16 v[124:127], v[48:51], v[188:191], v[124:127]
	v_mfma_f32_16x16x32_bf16 v[120:123], v[72:75], v[188:191], v[120:123]
	v_mfma_f32_16x16x32_bf16 v[116:119], v[48:51], v[196:199], v[116:119]
	v_mfma_f32_16x16x32_bf16 v[112:115], v[72:75], v[196:199], v[112:115]
	v_mfma_f32_16x16x32_bf16 v[100:103], v[48:51], v[214:217], v[100:103]
	v_mfma_f32_16x16x32_bf16 v[96:99], v[72:75], v[214:217], v[96:99]
	v_mfma_f32_16x16x32_bf16 v[140:143], v[52:55], v[184:187], v[140:143]
	v_mfma_f32_16x16x32_bf16 v[136:139], v[76:79], v[184:187], v[136:139]
	v_mfma_f32_16x16x32_bf16 v[124:127], v[52:55], v[192:195], v[124:127]
	v_mfma_f32_16x16x32_bf16 v[120:123], v[76:79], v[192:195], v[120:123]
	v_mfma_f32_16x16x32_bf16 v[116:119], v[52:55], v[210:213], v[116:119]
	v_mfma_f32_16x16x32_bf16 v[112:115], v[76:79], v[210:213], v[112:115]
	v_mfma_f32_16x16x32_bf16 v[100:103], v[52:55], v[218:221], v[100:103]
	v_mfma_f32_16x16x32_bf16 v[96:99], v[76:79], v[218:221], v[96:99]
	v_mfma_f32_16x16x32_bf16 v[132:135], v[162:165], v[180:183], v[132:135]
	v_mfma_f32_16x16x32_bf16 v[128:131], v[172:175], v[180:183], v[128:131]
	v_mfma_f32_16x16x32_bf16 v[108:111], v[162:165], v[188:191], v[108:111]
	v_mfma_f32_16x16x32_bf16 v[104:107], v[172:175], v[188:191], v[104:107]
	v_mfma_f32_16x16x32_bf16 v[92:95], v[162:165], v[196:199], v[92:95]
	v_mfma_f32_16x16x32_bf16 v[88:91], v[172:175], v[196:199], v[88:91]
	v_mfma_f32_16x16x32_bf16 v[84:87], v[162:165], v[214:217], v[84:87]
	v_mfma_f32_16x16x32_bf16 v[80:83], v[172:175], v[214:217], v[80:83]
	v_mfma_f32_16x16x32_bf16 v[132:135], v[168:171], v[184:187], v[132:135]
	v_mfma_f32_16x16x32_bf16 v[128:131], v[176:179], v[184:187], v[128:131]
	v_mfma_f32_16x16x32_bf16 v[108:111], v[168:171], v[192:195], v[108:111]
	v_mfma_f32_16x16x32_bf16 v[104:107], v[176:179], v[192:195], v[104:107]
	v_mfma_f32_16x16x32_bf16 v[92:95], v[168:171], v[210:213], v[92:95]
	v_mfma_f32_16x16x32_bf16 v[88:91], v[176:179], v[210:213], v[88:91]
	v_mfma_f32_16x16x32_bf16 v[84:87], v[168:171], v[218:221], v[84:87]
	v_mfma_f32_16x16x32_bf16 v[80:83], v[176:179], v[218:221], v[80:83]
	s_setprio 0
	s_barrier
	s_add_i32 s40, s40, s22
	v_lshl_add_u64 v[154:155], s[14:15], 0, v[160:161]
	s_mov_b32 m0, s40
	ds_read_b128 v[180:183], v159 offset:16384
	ds_read_b128 v[184:187], v159 offset:17408
	ds_read_b128 v[188:191], v159 offset:18432
	ds_read_b128 v[192:195], v159 offset:19456
	ds_read_b128 v[196:199], v159 offset:20480
	ds_read_b128 v[210:213], v159 offset:21504
	ds_read_b128 v[214:217], v159 offset:22528
	ds_read_b128 v[218:221], v159 offset:23552
	global_load_lds_dwordx4 v[154:155], off
	s_add_i32 m0, s40, 0x2000
	s_add_u32 s40, s14, 0x160000
	v_lshl_add_u64 v[222:223], s[14:15], 0, v[144:145]
	s_addc_u32 s41, s15, 0
	s_add_i32 s42, s42, s22
	global_load_lds_dwordx4 v[222:223], off
	v_lshl_add_u64 v[224:225], s[40:41], 0, v[160:161]
	s_mov_b32 m0, s42
	v_lshl_add_u64 v[226:227], s[16:17], 0, v[146:147]
	global_load_lds_dwordx4 v[224:225], off
	v_lshl_add_u64 v[224:225], s[40:41], 0, v[144:145]
	s_add_i32 m0, s42, 0x2000
	s_nop 0
	global_load_lds_dwordx4 v[224:225], off
	v_lshl_add_u64 v[224:225], s[16:17], 0, v[148:149]
	s_mov_b32 m0, s23
	s_nop 0
	global_load_lds_dwordx4 v[224:225], off
	s_mov_b32 m0, s24
	s_nop 0
	global_load_lds_dwordx4 v[226:227], off
	s_waitcnt vmcnt(8) lgkmcnt(0)
	s_barrier
; #define PG8_STAGE(bufoff, gbase, voff) do { _Pragma("unroll") for (int _i = 0; _i < 2; ++_i) \
;         __builtin_amdgcn_global_load_lds((const unsigned*)((const char*)(gbase) + (voff)[_i]), (LAS unsigned*)(lds + (bufoff) + ldsw + _i * 8192), 16, 0, 0); } while (0)
; #define PG8_LDA(dst, b, h) do { _Pragma("unroll") for (int m = 0; m < 4; ++m) _Pragma("unroll") for (int k = 0; k < 2; ++k) dst[m][k] = *(const LAS bf16x8*)(lds + PG8_SA(b, h) + aoff + m * 2048 + k * 1024); } while (0)
; #define PG8_LDB(dst, b, h) do { _Pragma("unroll") for (int n = 0; n < 2; ++n) _Pragma("unroll") for (int k = 0; k < 2; ++k) dst[n][k] = *(const LAS bf16x8*)(lds + PG8_SB(b, h) + boff + n * 2048 + k * 1024); } while (0)
; #define PG8_MMA(ai, bj, At, Bt) do { __builtin_amdgcn_s_setprio(1); _Pragma("unroll") for (int m = 0; m < 4; ++m) _Pragma("unroll") for (int n = 0; n < 2; ++n) _Pragma("unroll") for (int k = 0; k < 2; ++k) \
;         acc[ai][bj][m][n] = __builtin_amdgcn_mfma_f32_16x16x32_bf16(Bt[n][k], At[m][k], acc[ai][bj][m][n], 0, 0, 0); __builtin_amdgcn_s_setprio(0); } while (0)
; #define PG8_WAIT_V(n) asm volatile("s_waitcnt vmcnt(" #n ")" ::: "memory")
; #define PG8_WAIT_L(n) asm volatile("s_waitcnt lgkmcnt(" #n ")" ::: "memory")
; #define PG8_BAR __builtin_amdgcn_s_barrier()
; #define PG8_SCHED __builtin_amdgcn_sched_barrier(0)
; template <class Epi, class Sched>
; DI void gemm_phase(const int wv, LAS unsigned char* lds, const int lda, const int ldb, const int K, const Sched& S, const Epi& E) {
;     ...
;             PG8_WAIT_V(8); PG8_WAIT_L(0); PG8_BAR; PG8_MMA(1, 0, At, B0); PG8_MMA(1, 1, At, B1); PG8_BAR; PG8_SCHED;
;             PG8_LDB(B0, 1, 0); PG8_LDB(B1, 1, 1); PG8_SCHED; PG8_LDA(At, 1, 0); PG8_STAGE(PG8_SA(0, 1), a2 + hstepA, voffA);
;             PG8_WAIT_V(8); PG8_WAIT_L(0); PG8_BAR; PG8_MMA(0, 0, At, B0); PG8_MMA(0, 1, At, B1); PG8_BAR; PG8_SCHED;
	s_setprio 1
	v_mfma_f32_16x16x32_bf16 v[68:71], v[48:51], v[180:183], v[68:71]
	v_mfma_f32_16x16x32_bf16 v[64:67], v[72:75], v[180:183], v[64:67]
	v_mfma_f32_16x16x32_bf16 v[44:47], v[48:51], v[188:191], v[44:47]
	v_mfma_f32_16x16x32_bf16 v[40:43], v[72:75], v[188:191], v[40:43]
	v_mfma_f32_16x16x32_bf16 v[28:31], v[48:51], v[196:199], v[28:31]
	v_mfma_f32_16x16x32_bf16 v[24:27], v[72:75], v[196:199], v[24:27]
	v_mfma_f32_16x16x32_bf16 v[12:15], v[48:51], v[214:217], v[12:15]
	v_mfma_f32_16x16x32_bf16 v[8:11], v[72:75], v[214:217], v[8:11]
	v_mfma_f32_16x16x32_bf16 v[68:71], v[52:55], v[184:187], v[68:71]
	v_mfma_f32_16x16x32_bf16 v[64:67], v[76:79], v[184:187], v[64:67]
	v_mfma_f32_16x16x32_bf16 v[44:47], v[52:55], v[192:195], v[44:47]
	v_mfma_f32_16x16x32_bf16 v[40:43], v[76:79], v[192:195], v[40:43]
	v_mfma_f32_16x16x32_bf16 v[28:31], v[52:55], v[210:213], v[28:31]
	v_mfma_f32_16x16x32_bf16 v[24:27], v[76:79], v[210:213], v[24:27]
	v_mfma_f32_16x16x32_bf16 v[12:15], v[52:55], v[218:221], v[12:15]
	v_mfma_f32_16x16x32_bf16 v[8:11], v[76:79], v[218:221], v[8:11]
	v_mfma_f32_16x16x32_bf16 v[36:39], v[162:165], v[188:191], v[36:39]
	v_mfma_f32_16x16x32_bf16 v[32:35], v[172:175], v[188:191], v[32:35]
	v_mfma_f32_16x16x32_bf16 v[20:23], v[162:165], v[196:199], v[20:23]
	v_mfma_f32_16x16x32_bf16 v[16:19], v[172:175], v[196:199], v[16:19]
	v_mfma_f32_16x16x32_bf16 v[4:7], v[162:165], v[214:217], v[4:7]
	v_mfma_f32_16x16x32_bf16 v[0:3], v[172:175], v[214:217], v[0:3]
	v_mfma_f32_16x16x32_bf16 v[48:51], v[162:165], v[180:183], v[60:63]
	v_mfma_f32_16x16x32_bf16 v[52:55], v[172:175], v[180:183], v[56:59]
	v_mfma_f32_16x16x32_bf16 v[36:39], v[168:171], v[192:195], v[36:39]
	v_mfma_f32_16x16x32_bf16 v[32:35], v[176:179], v[192:195], v[32:35]
	v_mfma_f32_16x16x32_bf16 v[20:23], v[168:171], v[210:213], v[20:23]
	v_mfma_f32_16x16x32_bf16 v[16:19], v[176:179], v[210:213], v[16:19]
	v_mfma_f32_16x16x32_bf16 v[4:7], v[168:171], v[218:221], v[4:7]
	v_mfma_f32_16x16x32_bf16 v[0:3], v[176:179], v[218:221], v[0:3]
	v_mfma_f32_16x16x32_bf16 v[48:51], v[168:171], v[184:187], v[48:51]
	v_mfma_f32_16x16x32_bf16 v[52:55], v[176:179], v[184:187], v[52:55]
	s_setprio 0
	s_barrier
	s_add_i32 s40, 0, 0x18000
	s_add_i32 s41, 0, 0x1c000
	v_add_u32_e32 v76, s40, v157
	v_add_u32_e32 v176, s41, v157
	ds_read_b128 v[56:59], v76
	ds_read_b128 v[60:63], v76 offset:1024
	ds_read_b128 v[72:75], v76 offset:2048
	ds_read_b128 v[76:79], v76 offset:3072
	ds_read_b128 v[162:165], v176
	ds_read_b128 v[168:171], v176 offset:1024
	ds_read_b128 v[172:175], v176 offset:2048
	ds_read_b128 v[176:179], v176 offset:3072
	s_add_u32 s16, s16, 0x160000
	s_addc_u32 s17, s17, 0
	s_mov_b32 m0, s25
	v_lshl_add_u64 v[228:229], s[16:17], 0, v[148:149]
	ds_read_b128 v[180:183], v159 offset:32768
	ds_read_b128 v[184:187], v159 offset:33792
	ds_read_b128 v[188:191], v159 offset:34816
	ds_read_b128 v[192:195], v159 offset:35840
	ds_read_b128 v[196:199], v159 offset:36864
	ds_read_b128 v[210:213], v159 offset:37888
	ds_read_b128 v[214:217], v159 offset:38912
	ds_read_b128 v[218:221], v159 offset:39936
	global_load_lds_dwordx4 v[228:229], off
	v_lshl_add_u64 v[228:229], s[16:17], 0, v[146:147]
	s_mov_b32 m0, s26
	s_nop 0
	global_load_lds_dwordx4 v[228:229], off
	s_waitcnt vmcnt(8) lgkmcnt(0)
	s_barrier
	s_setprio 1
	v_mfma_f32_16x16x32_bf16 v[140:143], v[56:59], v[180:183], v[140:143]
	v_mfma_f32_16x16x32_bf16 v[136:139], v[72:75], v[180:183], v[136:139]
	v_mfma_f32_16x16x32_bf16 v[124:127], v[56:59], v[188:191], v[124:127]
	v_mfma_f32_16x16x32_bf16 v[120:123], v[72:75], v[188:191], v[120:123]
	v_mfma_f32_16x16x32_bf16 v[116:119], v[56:59], v[196:199], v[116:119]
	v_mfma_f32_16x16x32_bf16 v[112:115], v[72:75], v[196:199], v[112:115]
	v_mfma_f32_16x16x32_bf16 v[100:103], v[56:59], v[214:217], v[100:103]
	v_mfma_f32_16x16x32_bf16 v[96:99], v[72:75], v[214:217], v[96:99]
	v_mfma_f32_16x16x32_bf16 v[140:143], v[60:63], v[184:187], v[140:143]
	v_mfma_f32_16x16x32_bf16 v[136:139], v[76:79], v[184:187], v[136:139]
	v_mfma_f32_16x16x32_bf16 v[124:127], v[60:63], v[192:195], v[124:127]
	v_mfma_f32_16x16x32_bf16 v[120:123], v[76:79], v[192:195], v[120:123]
	v_mfma_f32_16x16x32_bf16 v[116:119], v[60:63], v[210:213], v[116:119]
	v_mfma_f32_16x16x32_bf16 v[112:115], v[76:79], v[210:213], v[112:115]
	v_mfma_f32_16x16x32_bf16 v[100:103], v[60:63], v[218:221], v[100:103]
	v_mfma_f32_16x16x32_bf16 v[96:99], v[76:79], v[218:221], v[96:99]
	v_mfma_f32_16x16x32_bf16 v[132:135], v[162:165], v[180:183], v[132:135]
	v_mfma_f32_16x16x32_bf16 v[128:131], v[172:175], v[180:183], v[128:131]
	v_mfma_f32_16x16x32_bf16 v[108:111], v[162:165], v[188:191], v[108:111]
	v_mfma_f32_16x16x32_bf16 v[104:107], v[172:175], v[188:191], v[104:107]
	v_mfma_f32_16x16x32_bf16 v[92:95], v[162:165], v[196:199], v[92:95]
	v_mfma_f32_16x16x32_bf16 v[88:91], v[172:175], v[196:199], v[88:91]
	v_mfma_f32_16x16x32_bf16 v[84:87], v[162:165], v[214:217], v[84:87]
	v_mfma_f32_16x16x32_bf16 v[80:83], v[172:175], v[214:217], v[80:83]
	v_mfma_f32_16x16x32_bf16 v[132:135], v[168:171], v[184:187], v[132:135]
	v_mfma_f32_16x16x32_bf16 v[128:131], v[176:179], v[184:187], v[128:131]
	v_mfma_f32_16x16x32_bf16 v[108:111], v[168:171], v[192:195], v[108:111]
	v_mfma_f32_16x16x32_bf16 v[104:107], v[176:179], v[192:195], v[104:107]
	v_mfma_f32_16x16x32_bf16 v[92:95], v[168:171], v[210:213], v[92:95]
	v_mfma_f32_16x16x32_bf16 v[88:91], v[176:179], v[210:213], v[88:91]
	v_mfma_f32_16x16x32_bf16 v[84:87], v[168:171], v[218:221], v[84:87]
	v_mfma_f32_16x16x32_bf16 v[80:83], v[176:179], v[218:221], v[80:83]
	s_setprio 0
	s_barrier
; #define PG8_STAGE(bufoff, gbase, voff) do { _Pragma("unroll") for (int _i = 0; _i < 2; ++_i) \
;         __builtin_amdgcn_global_load_lds((const unsigned*)((const char*)(gbase) + (voff)[_i]), (LAS unsigned*)(lds + (bufoff) + ldsw + _i * 8192), 16, 0, 0); } while (0)
; #define PG8_LDA(dst, b, h) do { _Pragma("unroll") for (int m = 0; m < 4; ++m) _Pragma("unroll") for (int k = 0; k < 2; ++k) dst[m][k] = *(const LAS bf16x8*)(lds + PG8_SA(b, h) + aoff + m * 2048 + k * 1024); } while (0)
; #define PG8_MMA(ai, bj, At, Bt) do { __builtin_amdgcn_s_setprio(1); _Pragma("unroll") for (int m = 0; m < 4; ++m) _Pragma("unroll") for (int n = 0; n < 2; ++n) _Pragma("unroll") for (int k = 0; k < 2; ++k) \
;         acc[ai][bj][m][n] = __builtin_amdgcn_mfma_f32_16x16x32_bf16(Bt[n][k], At[m][k], acc[ai][bj][m][n], 0, 0, 0); __builtin_amdgcn_s_setprio(0); } while (0)
; #define PG8_WAIT_V(n) asm volatile("s_waitcnt vmcnt(" #n ")" ::: "memory")
; #define PG8_WAIT_L(n) asm volatile("s_waitcnt lgkmcnt(" #n ")" ::: "memory")
; #define PG8_BAR __builtin_amdgcn_s_barrier()
; #define PG8_SCHED __builtin_amdgcn_sched_barrier(0)
; template <class Epi, class Sched>
; DI void gemm_phase(const int wv, LAS unsigned char* lds, const int lda, const int ldb, const int K, const Sched& S, const Epi& E) {
;     ...
;             PG8_LDA(At, 1, 1); PG8_STAGE(PG8_SB(1, 0), b3, voffB); PG8_STAGE(PG8_SB(1, 1), b3 + hstepB, voffB); PG8_STAGE(PG8_SA(1, 0), a3, voffA);
;             PG8_WAIT_V(8); PG8_WAIT_L(0); PG8_BAR; PG8_MMA(1, 0, At, B0); PG8_MMA(1, 1, At, B1); PG8_BAR; PG8_SCHED;
;         }
;         if (wr == 0) PG8_BAR;
	s_add_i32 s16, s40, s22
	v_lshl_add_u64 v[154:155], v[154:155], 0, s[78:79]
	s_mov_b32 m0, s16
	ds_read_b128 v[180:183], v159 offset:49152
	ds_read_b128 v[184:187], v159 offset:50176
	ds_read_b128 v[188:191], v159 offset:51200
	ds_read_b128 v[192:195], v159 offset:52224
	ds_read_b128 v[196:199], v159 offset:53248
	ds_read_b128 v[210:213], v159 offset:54272
	ds_read_b128 v[214:217], v159 offset:55296
	ds_read_b128 v[218:221], v159 offset:56320
	global_load_lds_dwordx4 v[154:155], off
	s_add_i32 m0, s16, 0x2000
	s_add_u32 s14, s14, 0x160080
	v_lshl_add_u64 v[154:155], v[222:223], 0, s[78:79]
	s_addc_u32 s15, s15, 0
	s_add_i32 s16, s41, s22
	global_load_lds_dwordx4 v[154:155], off
	v_lshl_add_u64 v[154:155], s[14:15], 0, v[160:161]
	s_mov_b32 m0, s16
	s_nop 0
	global_load_lds_dwordx4 v[154:155], off
	v_lshl_add_u64 v[154:155], s[14:15], 0, v[144:145]
	s_add_i32 m0, s16, 0x2000
	s_nop 0
	global_load_lds_dwordx4 v[154:155], off
	v_lshl_add_u64 v[154:155], v[224:225], 0, s[78:79]
	s_mov_b32 m0, s29
	s_nop 0
	global_load_lds_dwordx4 v[154:155], off
	v_lshl_add_u64 v[154:155], v[226:227], 0, s[78:79]
	s_mov_b32 m0, s30
	s_nop 0
	global_load_lds_dwordx4 v[154:155], off
	s_waitcnt vmcnt(8) lgkmcnt(0)
	s_barrier
	s_setprio 1
	v_mfma_f32_16x16x32_bf16 v[68:71], v[56:59], v[180:183], v[68:71]
	v_mfma_f32_16x16x32_bf16 v[64:67], v[72:75], v[180:183], v[64:67]
	v_mfma_f32_16x16x32_bf16 v[44:47], v[56:59], v[188:191], v[44:47]
	v_mfma_f32_16x16x32_bf16 v[40:43], v[72:75], v[188:191], v[40:43]
	v_mfma_f32_16x16x32_bf16 v[28:31], v[56:59], v[196:199], v[28:31]
	v_mfma_f32_16x16x32_bf16 v[24:27], v[72:75], v[196:199], v[24:27]
	v_mfma_f32_16x16x32_bf16 v[12:15], v[56:59], v[214:217], v[12:15]
	v_mfma_f32_16x16x32_bf16 v[8:11], v[72:75], v[214:217], v[8:11]
	v_mfma_f32_16x16x32_bf16 v[68:71], v[60:63], v[184:187], v[68:71]
	v_mfma_f32_16x16x32_bf16 v[64:67], v[76:79], v[184:187], v[64:67]
	v_mfma_f32_16x16x32_bf16 v[44:47], v[60:63], v[192:195], v[44:47]
	v_mfma_f32_16x16x32_bf16 v[40:43], v[76:79], v[192:195], v[40:43]
	v_mfma_f32_16x16x32_bf16 v[28:31], v[60:63], v[210:213], v[28:31]
	v_mfma_f32_16x16x32_bf16 v[24:27], v[76:79], v[210:213], v[24:27]
	v_mfma_f32_16x16x32_bf16 v[12:15], v[60:63], v[218:221], v[12:15]
	v_mfma_f32_16x16x32_bf16 v[8:11], v[76:79], v[218:221], v[8:11]
	v_mfma_f32_16x16x32_bf16 v[48:51], v[162:165], v[180:183], v[48:51]
	v_mfma_f32_16x16x32_bf16 v[60:63], v[168:171], v[184:187], v[48:51]
	v_mfma_f32_16x16x32_bf16 v[48:51], v[172:175], v[180:183], v[52:55]
	v_mfma_f32_16x16x32_bf16 v[36:39], v[162:165], v[188:191], v[36:39]
	v_mfma_f32_16x16x32_bf16 v[32:35], v[172:175], v[188:191], v[32:35]
	v_mfma_f32_16x16x32_bf16 v[20:23], v[162:165], v[196:199], v[20:23]
	v_mfma_f32_16x16x32_bf16 v[16:19], v[172:175], v[196:199], v[16:19]
	v_mfma_f32_16x16x32_bf16 v[4:7], v[162:165], v[214:217], v[4:7]
	v_mfma_f32_16x16x32_bf16 v[0:3], v[172:175], v[214:217], v[0:3]
	v_mfma_f32_16x16x32_bf16 v[56:59], v[176:179], v[184:187], v[48:51]
	v_mfma_f32_16x16x32_bf16 v[36:39], v[168:171], v[192:195], v[36:39]
	v_mfma_f32_16x16x32_bf16 v[32:35], v[176:179], v[192:195], v[32:35]
	v_mfma_f32_16x16x32_bf16 v[20:23], v[168:171], v[210:213], v[20:23]
	v_mfma_f32_16x16x32_bf16 v[16:19], v[176:179], v[210:213], v[16:19]
	v_mfma_f32_16x16x32_bf16 v[4:7], v[168:171], v[218:221], v[4:7]
	v_mfma_f32_16x16x32_bf16 v[0:3], v[176:179], v[218:221], v[0:3]
	s_setprio 0
	s_barrier
	s_add_i32 s39, s39, 2
	s_add_u32 s37, s37, 0x100
	s_addc_u32 s38, s38, 0
	s_add_u32 s12, s12, 0x100
	s_addc_u32 s13, s13, 0
	s_cmpk_gt_u32 s39, 0x55
	s_cbranch_scc0 .LBB0_906
	s_and_b64 vcc, exec, s[6:7]
	s_cbranch_vccz .LBB0_909
	s_barrier
